# conv_layer transposes: 16 loads in flight per wave (was 2), counted vmcnt before LDS writes
# speedup vs baseline: 1.0093x; 1.0035x over previous
; __device__ __forceinline__ void transpose_item(const float* __restrict__ W, int K, int N, bf16_t* __restrict__ WT, LAS float* scr, int item, int lane, bool ffn_remap = false) {
;     ...
; #pragma unroll 8
;     for (int i = 0; i < 32; ++i) { const int kk = 2 * i + (lane >> 5); scr[kk * 33 + (lane & 31)] = W[(size_t)(k0 + kk) * N + n0 + (lane & 31)]; }
.LBB0_289:
	s_lshl_b32 s15, s3, 1
	s_lshl_b32 s13, s2, 1
	v_or_b32_e32 v48, s15, v0
	v_or_b32_e32 v46, s13, v7
	v_ashrrev_i32_e32 v49, 31, v48
	v_ashrrev_i32_e32 v47, 31, v46
	v_lshlrev_b64 v[48:49], 13, v[48:49]
	v_lshlrev_b64 v[46:47], 13, v[46:47]
	v_lshl_add_u64 v[48:49], v[38:39], 0, v[48:49]
	v_lshl_add_u64 v[46:47], v[38:39], 0, v[46:47]
	global_load_dword v100, v[48:49], off
	global_load_dword v101, v[46:47], off
	v_or_b32_e32 v40, s13, v5
	v_or_b32_e32 v45, s15, v4
	v_mad_u64_u32 v[116:117], s[16:17], v45, s37, v[8:9]
	v_mad_u64_u32 v[118:119], s[16:17], v40, s37, v[8:9]
	s_add_i32 s17, s15, 4
	s_add_i32 s16, s13, 4
	v_or_b32_e32 v40, s16, v5
	v_or_b32_e32 v45, s17, v4
	s_add_i32 s3, s3, 16
	s_add_i32 s2, s2, 16
	s_add_i32 s4, s4, -16
	v_or_b32_e32 v48, s17, v0
	v_or_b32_e32 v46, s16, v7
	v_ashrrev_i32_e32 v49, 31, v48
	v_ashrrev_i32_e32 v47, 31, v46
	v_lshlrev_b64 v[48:49], 13, v[48:49]
	v_lshlrev_b64 v[46:47], 13, v[46:47]
	v_lshl_add_u64 v[48:49], v[38:39], 0, v[48:49]
	v_lshl_add_u64 v[46:47], v[38:39], 0, v[46:47]
	global_load_dword v102, v[48:49], off
	global_load_dword v103, v[46:47], off
	v_mad_u64_u32 v[120:121], s[16:17], v45, s37, v[8:9]
	v_mad_u64_u32 v[122:123], s[16:17], v40, s37, v[8:9]
	s_add_i32 s17, s15, 8
	s_add_i32 s16, s13, 8
	v_or_b32_e32 v40, s16, v5
	v_or_b32_e32 v45, s17, v4
	v_or_b32_e32 v48, s17, v0
	v_or_b32_e32 v46, s16, v7
	v_ashrrev_i32_e32 v49, 31, v48
	v_ashrrev_i32_e32 v47, 31, v46
	v_lshlrev_b64 v[48:49], 13, v[48:49]
	v_lshlrev_b64 v[46:47], 13, v[46:47]
	v_lshl_add_u64 v[48:49], v[38:39], 0, v[48:49]
	v_lshl_add_u64 v[46:47], v[38:39], 0, v[46:47]
	global_load_dword v104, v[48:49], off
	global_load_dword v105, v[46:47], off
	v_mad_u64_u32 v[124:125], s[16:17], v45, s37, v[8:9]
	v_mad_u64_u32 v[126:127], s[16:17], v40, s37, v[8:9]
	s_add_i32 s17, s15, 12
	s_add_i32 s16, s13, 12
	v_or_b32_e32 v40, s16, v5
	v_or_b32_e32 v45, s17, v4
	v_or_b32_e32 v48, s17, v0
	v_or_b32_e32 v46, s16, v7
	v_ashrrev_i32_e32 v49, 31, v48
	v_ashrrev_i32_e32 v47, 31, v46
	v_lshlrev_b64 v[48:49], 13, v[48:49]
	v_lshlrev_b64 v[46:47], 13, v[46:47]
	v_lshl_add_u64 v[48:49], v[38:39], 0, v[48:49]
	v_lshl_add_u64 v[46:47], v[38:39], 0, v[46:47]
	global_load_dword v106, v[48:49], off
	global_load_dword v107, v[46:47], off
	v_mad_u64_u32 v[128:129], s[16:17], v45, s37, v[8:9]
	v_mad_u64_u32 v[130:131], s[16:17], v40, s37, v[8:9]
	s_add_i32 s17, s15, 16
	s_add_i32 s16, s13, 16
	v_or_b32_e32 v40, s16, v5
	v_or_b32_e32 v45, s17, v4
	v_or_b32_e32 v48, s17, v0
	v_or_b32_e32 v46, s16, v7
	v_ashrrev_i32_e32 v49, 31, v48
	v_ashrrev_i32_e32 v47, 31, v46
	v_lshlrev_b64 v[48:49], 13, v[48:49]
	v_lshlrev_b64 v[46:47], 13, v[46:47]
	v_lshl_add_u64 v[48:49], v[38:39], 0, v[48:49]
	v_lshl_add_u64 v[46:47], v[38:39], 0, v[46:47]
	global_load_dword v108, v[48:49], off
	global_load_dword v109, v[46:47], off
	v_mad_u64_u32 v[132:133], s[16:17], v45, s37, v[8:9]
	v_mad_u64_u32 v[134:135], s[16:17], v40, s37, v[8:9]
	s_add_i32 s17, s15, 20
	s_add_i32 s16, s13, 20
	v_or_b32_e32 v40, s16, v5
	v_or_b32_e32 v45, s17, v4
	v_or_b32_e32 v48, s17, v0
	v_or_b32_e32 v46, s16, v7
	v_ashrrev_i32_e32 v49, 31, v48
	v_ashrrev_i32_e32 v47, 31, v46
	v_lshlrev_b64 v[48:49], 13, v[48:49]
	v_lshlrev_b64 v[46:47], 13, v[46:47]
	v_lshl_add_u64 v[48:49], v[38:39], 0, v[48:49]
	v_lshl_add_u64 v[46:47], v[38:39], 0, v[46:47]
	global_load_dword v110, v[48:49], off
	global_load_dword v111, v[46:47], off
	v_mad_u64_u32 v[136:137], s[16:17], v45, s37, v[8:9]
	v_mad_u64_u32 v[138:139], s[16:17], v40, s37, v[8:9]
	s_add_i32 s17, s15, 24
	s_add_i32 s16, s13, 24
	v_or_b32_e32 v40, s16, v5
	v_or_b32_e32 v45, s17, v4
	s_add_i32 s15, s15, 28
	s_add_i32 s13, s13, 28
	s_cmp_lg_u32 s4, 0
	v_or_b32_e32 v48, s17, v0
	v_or_b32_e32 v46, s16, v7
	v_ashrrev_i32_e32 v49, 31, v48
	v_ashrrev_i32_e32 v47, 31, v46
	v_lshlrev_b64 v[48:49], 13, v[48:49]
	v_lshlrev_b64 v[46:47], 13, v[46:47]
	v_lshl_add_u64 v[48:49], v[38:39], 0, v[48:49]
	v_lshl_add_u64 v[46:47], v[38:39], 0, v[46:47]
	global_load_dword v112, v[48:49], off
	global_load_dword v113, v[46:47], off
	v_mad_u64_u32 v[140:141], s[16:17], v45, s37, v[8:9]
	v_mad_u64_u32 v[142:143], s[16:17], v40, s37, v[8:9]
	v_or_b32_e32 v45, s15, v4
	v_or_b32_e32 v40, s13, v5
	v_or_b32_e32 v48, s15, v0
	v_or_b32_e32 v46, s13, v7
	v_ashrrev_i32_e32 v49, 31, v48
	v_ashrrev_i32_e32 v47, 31, v46
	v_lshlrev_b64 v[48:49], 13, v[48:49]
	v_lshlrev_b64 v[46:47], 13, v[46:47]
	v_lshl_add_u64 v[48:49], v[38:39], 0, v[48:49]
	v_lshl_add_u64 v[46:47], v[38:39], 0, v[46:47]
	global_load_dword v114, v[48:49], off
	global_load_dword v115, v[46:47], off
	v_mad_u64_u32 v[144:145], s[16:17], v45, s37, v[8:9]
	v_mad_u64_u32 v[146:147], s[16:17], v40, s37, v[8:9]
	s_waitcnt vmcnt(15)
	ds_write_b32 v116, v100
	s_waitcnt vmcnt(14)
	ds_write_b32 v118, v101
	s_waitcnt vmcnt(13)
	ds_write_b32 v120, v102
	s_waitcnt vmcnt(12)
	ds_write_b32 v122, v103
	s_waitcnt vmcnt(11)
	ds_write_b32 v124, v104
	s_waitcnt vmcnt(10)
	ds_write_b32 v126, v105
	s_waitcnt vmcnt(9)
	ds_write_b32 v128, v106
	s_waitcnt vmcnt(8)
	ds_write_b32 v130, v107
	s_waitcnt vmcnt(7)
	ds_write_b32 v132, v108
	s_waitcnt vmcnt(6)
	ds_write_b32 v134, v109
	s_waitcnt vmcnt(5)
	ds_write_b32 v136, v110
	s_waitcnt vmcnt(4)
	ds_write_b32 v138, v111
	s_waitcnt vmcnt(3)
	ds_write_b32 v140, v112
	s_waitcnt vmcnt(2)
	ds_write_b32 v142, v113
	s_waitcnt vmcnt(1)
	ds_write_b32 v144, v114
	s_waitcnt vmcnt(0)
	ds_write_b32 v146, v115
	s_cbranch_scc1 .LBB0_289
; #define LAS __attribute__((address_space(3)))
; __device__ __forceinline__ unsigned pk2(float lo, float hi) { f32x2_t v = {lo, hi}; bf16x2_t b = __builtin_convertvector(v, bf16x2_t); return __builtin_bit_cast(unsigned, b); }
; __device__ __forceinline__ void transpose_item(const float* __restrict__ W, int K, int N, bf16_t* __restrict__ WT, LAS float* scr, int item, int lane, bool ffn_remap = false) {
;     ...
;     const int c = lane & 7;
; #pragma unroll
;     for (int j = 0; j < 4; ++j) { const int n = (lane >> 3) + 8 * j; const LAS float* s = scr + (8 * c) * 33 + n;
;         u32x4 o; o.x = pk2(s[0 * 33], s[1 * 33]); o.y = pk2(s[2 * 33], s[3 * 33]); o.z = pk2(s[4 * 33], s[5 * 33]); o.w = pk2(s[6 * 33], s[7 * 33]);
;         *(u32x4*)(WT + (size_t)(d0 + n) * K + k0 + 8 * c) = o; }
;     asm volatile("s_waitcnt lgkmcnt(0)" ::: "memory");
	s_waitcnt lgkmcnt(0)
	ds_read2_b32 v[50:51], v41 offset0:33 offset1:41
	ds_read2_b32 v[52:53], v41 offset1:8
	ds_read2_b32 v[54:55], v41 offset0:66 offset1:74
	ds_read2_b32 v[56:57], v41 offset0:99 offset1:107
	ds_read2_b32 v[58:59], v41 offset0:132 offset1:140
	ds_read2_b32 v[60:61], v41 offset0:165 offset1:173
	ds_read2_b32 v[62:63], v41 offset0:198 offset1:206
	ds_read2_b32 v[64:65], v41 offset0:231 offset1:239
	v_or_b32_e32 v66, s12, v9
	s_ashr_i32 s27, s26, 31
	v_ashrrev_i32_e32 v67, 31, v66
	v_lshl_add_u64 v[38:39], s[26:27], 1, v[10:11]
	v_lshlrev_b64 v[66:67], 9, v[66:67]
	s_waitcnt lgkmcnt(6)
	v_cvt_pk_bf16_f32 v46, v52, v50
	s_waitcnt lgkmcnt(4)
	v_cvt_pk_bf16_f32 v47, v54, v56
	s_waitcnt lgkmcnt(2)
	v_cvt_pk_bf16_f32 v48, v58, v60
	s_waitcnt lgkmcnt(0)
	v_cvt_pk_bf16_f32 v49, v62, v64
	v_lshl_add_u64 v[66:67], v[38:39], 0, v[66:67]
	v_or_b32_e32 v50, s12, v42
	global_store_dwordx4 v[66:67], v[46:49], off
	v_or_b32_e32 v66, s12, v43
	v_ashrrev_i32_e32 v67, 31, v66
	v_cvt_pk_bf16_f32 v46, v53, v51
	v_ashrrev_i32_e32 v51, 31, v50
	v_lshlrev_b64 v[50:51], 9, v[50:51]
	v_cvt_pk_bf16_f32 v47, v55, v57
	v_cvt_pk_bf16_f32 v48, v59, v61
	v_cvt_pk_bf16_f32 v49, v63, v65
	v_lshl_add_u64 v[50:51], v[38:39], 0, v[50:51]
	global_store_dwordx4 v[50:51], v[46:49], off
	ds_read2_b32 v[50:51], v41 offset0:49 offset1:57
	ds_read2_b32 v[52:53], v41 offset0:16 offset1:24
	ds_read2_b32 v[54:55], v41 offset0:82 offset1:90
	ds_read2_b32 v[56:57], v41 offset0:115 offset1:123
	ds_read2_b32 v[58:59], v41 offset0:148 offset1:156
	ds_read2_b32 v[60:61], v41 offset0:181 offset1:189
	ds_read2_b32 v[62:63], v41 offset0:214 offset1:222
	ds_read2_b32 v[64:65], v41 offset0:247 offset1:255
	v_lshlrev_b64 v[66:67], 9, v[66:67]
	s_waitcnt lgkmcnt(6)
	v_cvt_pk_bf16_f32 v46, v52, v50
	s_waitcnt lgkmcnt(4)
	v_cvt_pk_bf16_f32 v47, v54, v56
	s_waitcnt lgkmcnt(2)
	v_cvt_pk_bf16_f32 v48, v58, v60
	s_waitcnt lgkmcnt(0)
	v_cvt_pk_bf16_f32 v49, v62, v64
	v_lshl_add_u64 v[66:67], v[38:39], 0, v[66:67]
	v_or_b32_e32 v50, s12, v44
	global_store_dwordx4 v[66:67], v[46:49], off
	s_nop 1
	v_cvt_pk_bf16_f32 v46, v53, v51
	v_ashrrev_i32_e32 v51, 31, v50
	v_lshlrev_b64 v[50:51], 9, v[50:51]
	v_cvt_pk_bf16_f32 v47, v55, v57
	v_cvt_pk_bf16_f32 v48, v59, v61
	v_cvt_pk_bf16_f32 v49, v63, v65
	v_lshl_add_u64 v[38:39], v[38:39], 0, v[50:51]
	global_store_dwordx4 v[38:39], v[46:49], off
	s_waitcnt lgkmcnt(0)

; #define LAS __attribute__((address_space(3)))
; __device__ __forceinline__ unsigned pk2(float lo, float hi) { f32x2_t v = {lo, hi}; bf16x2_t b = __builtin_convertvector(v, bf16x2_t); return __builtin_bit_cast(unsigned, b); }
; __device__ __forceinline__ void transpose_item(const float* __restrict__ W, int K, int N, bf16_t* __restrict__ WT, LAS float* scr, int item, int lane, bool ffn_remap = false) {
;     const int nblk = N / 32, kb = item / nblk, nb = item % nblk, k0 = 64 * kb, n0 = 32 * nb;
;     const int d0 = !ffn_remap ? n0 : (n0 < 4096 ? (n0 >> 7) * 256 + (n0 & 127) : ((n0 - 4096) >> 7) * 256 + 128 + (n0 & 127));
; #pragma unroll 8
;     for (int i = 0; i < 32; ++i) { const int kk = 2 * i + (lane >> 5); scr[kk * 33 + (lane & 31)] = W[(size_t)(k0 + kk) * N + n0 + (lane & 31)]; }
;     asm volatile("s_waitcnt lgkmcnt(0)" ::: "memory");
;     const int c = lane & 7;
; #pragma unroll
;     for (int j = 0; j < 4; ++j) { const int n = (lane >> 3) + 8 * j; const LAS float* s = scr + (8 * c) * 33 + n;
;         u32x4 o; o.x = pk2(s[0 * 33], s[1 * 33]); o.y = pk2(s[2 * 33], s[3 * 33]); o.z = pk2(s[4 * 33], s[5 * 33]); o.w = pk2(s[6 * 33], s[7 * 33]);
;         *(u32x4*)(WT + (size_t)(d0 + n) * K + k0 + 8 * c) = o; }
;     asm volatile("s_waitcnt lgkmcnt(0)" ::: "memory");
.LBB0_294:
	s_lshl_b32 s15, s5, 1
	s_lshl_b32 s13, s3, 1
	v_or_b32_e32 v46, s15, v0
	v_or_b32_e32 v48, s13, v7
	v_mad_i64_i32 v[46:47], s[16:17], v46, s63, v[38:39]
	v_mad_i64_i32 v[48:49], s[16:17], v48, s63, v[38:39]
	global_load_dword v100, v[46:47], off
	global_load_dword v101, v[48:49], off
	v_or_b32_e32 v40, s13, v5
	v_or_b32_e32 v45, s15, v4
	v_mad_u64_u32 v[116:117], s[16:17], v45, s37, v[8:9]
	v_mad_u64_u32 v[118:119], s[16:17], v40, s37, v[8:9]
	s_add_i32 s17, s15, 4
	s_add_i32 s16, s13, 4
	v_or_b32_e32 v40, s16, v5
	v_or_b32_e32 v45, s17, v4
	s_add_i32 s5, s5, 16
	s_add_i32 s3, s3, 16
	s_add_i32 s12, s12, -16
	v_or_b32_e32 v46, s17, v0
	v_or_b32_e32 v48, s16, v7
	v_mad_i64_i32 v[46:47], s[16:17], v46, s63, v[38:39]
	v_mad_i64_i32 v[48:49], s[16:17], v48, s63, v[38:39]
	global_load_dword v102, v[46:47], off
	global_load_dword v103, v[48:49], off
	v_mad_u64_u32 v[120:121], s[16:17], v45, s37, v[8:9]
	v_mad_u64_u32 v[122:123], s[16:17], v40, s37, v[8:9]
	s_add_i32 s17, s15, 8
	s_add_i32 s16, s13, 8
	v_or_b32_e32 v40, s16, v5
	v_or_b32_e32 v45, s17, v4
	v_or_b32_e32 v46, s17, v0
	v_or_b32_e32 v48, s16, v7
	v_mad_i64_i32 v[46:47], s[16:17], v46, s63, v[38:39]
	v_mad_i64_i32 v[48:49], s[16:17], v48, s63, v[38:39]
	global_load_dword v104, v[46:47], off
	global_load_dword v105, v[48:49], off
	v_mad_u64_u32 v[124:125], s[16:17], v45, s37, v[8:9]
	v_mad_u64_u32 v[126:127], s[16:17], v40, s37, v[8:9]
	s_add_i32 s17, s15, 12
	s_add_i32 s16, s13, 12
	v_or_b32_e32 v40, s16, v5
	v_or_b32_e32 v45, s17, v4
	v_or_b32_e32 v46, s17, v0
	v_or_b32_e32 v48, s16, v7
	v_mad_i64_i32 v[46:47], s[16:17], v46, s63, v[38:39]
	v_mad_i64_i32 v[48:49], s[16:17], v48, s63, v[38:39]
	global_load_dword v106, v[46:47], off
	global_load_dword v107, v[48:49], off
	v_mad_u64_u32 v[128:129], s[16:17], v45, s37, v[8:9]
	v_mad_u64_u32 v[130:131], s[16:17], v40, s37, v[8:9]
	s_add_i32 s17, s15, 16
	s_add_i32 s16, s13, 16
	v_or_b32_e32 v40, s16, v5
	v_or_b32_e32 v45, s17, v4
	v_or_b32_e32 v46, s17, v0
	v_or_b32_e32 v48, s16, v7
	v_mad_i64_i32 v[46:47], s[16:17], v46, s63, v[38:39]
	v_mad_i64_i32 v[48:49], s[16:17], v48, s63, v[38:39]
	global_load_dword v108, v[46:47], off
	global_load_dword v109, v[48:49], off
	v_mad_u64_u32 v[132:133], s[16:17], v45, s37, v[8:9]
	v_mad_u64_u32 v[134:135], s[16:17], v40, s37, v[8:9]
	s_add_i32 s17, s15, 20
	s_add_i32 s16, s13, 20
	v_or_b32_e32 v40, s16, v5
	v_or_b32_e32 v45, s17, v4
	v_or_b32_e32 v46, s17, v0
	v_or_b32_e32 v48, s16, v7
	v_mad_i64_i32 v[46:47], s[16:17], v46, s63, v[38:39]
	v_mad_i64_i32 v[48:49], s[16:17], v48, s63, v[38:39]
	global_load_dword v110, v[46:47], off
	global_load_dword v111, v[48:49], off
	v_mad_u64_u32 v[136:137], s[16:17], v45, s37, v[8:9]
	v_mad_u64_u32 v[138:139], s[16:17], v40, s37, v[8:9]
	s_add_i32 s17, s15, 24
	s_add_i32 s16, s13, 24
	v_or_b32_e32 v40, s16, v5
	v_or_b32_e32 v45, s17, v4
	s_add_i32 s15, s15, 28
	s_add_i32 s13, s13, 28
	s_cmp_lg_u32 s12, 0
	v_or_b32_e32 v46, s17, v0
	v_or_b32_e32 v48, s16, v7
	v_mad_i64_i32 v[46:47], s[16:17], v46, s63, v[38:39]
	v_mad_i64_i32 v[48:49], s[16:17], v48, s63, v[38:39]
	global_load_dword v112, v[46:47], off
	global_load_dword v113, v[48:49], off
	v_mad_u64_u32 v[140:141], s[16:17], v45, s37, v[8:9]
	v_mad_u64_u32 v[142:143], s[16:17], v40, s37, v[8:9]
	v_or_b32_e32 v45, s15, v4
	v_or_b32_e32 v40, s13, v5
	v_or_b32_e32 v46, s15, v0
	v_or_b32_e32 v48, s13, v7
	v_mad_i64_i32 v[46:47], s[16:17], v46, s63, v[38:39]
	v_mad_i64_i32 v[48:49], s[16:17], v48, s63, v[38:39]
	global_load_dword v114, v[46:47], off
	global_load_dword v115, v[48:49], off
	v_mad_u64_u32 v[144:145], s[16:17], v45, s37, v[8:9]
	v_mad_u64_u32 v[146:147], s[16:17], v40, s37, v[8:9]
	s_waitcnt vmcnt(15)
	ds_write_b32 v116, v100
	s_waitcnt vmcnt(14)
	ds_write_b32 v118, v101
	s_waitcnt vmcnt(13)
	ds_write_b32 v120, v102
	s_waitcnt vmcnt(12)
	ds_write_b32 v122, v103
	s_waitcnt vmcnt(11)
	ds_write_b32 v124, v104
	s_waitcnt vmcnt(10)
	ds_write_b32 v126, v105
	s_waitcnt vmcnt(9)
	ds_write_b32 v128, v106
	s_waitcnt vmcnt(8)
	ds_write_b32 v130, v107
	s_waitcnt vmcnt(7)
	ds_write_b32 v132, v108
	s_waitcnt vmcnt(6)
	ds_write_b32 v134, v109
	s_waitcnt vmcnt(5)
	ds_write_b32 v136, v110
	s_waitcnt vmcnt(4)
	ds_write_b32 v138, v111
	s_waitcnt vmcnt(3)
	ds_write_b32 v140, v112
	s_waitcnt vmcnt(2)
	ds_write_b32 v142, v113
	s_waitcnt vmcnt(1)
	ds_write_b32 v144, v114
	s_waitcnt vmcnt(0)
	ds_write_b32 v146, v115
	s_cbranch_scc1 .LBB0_294
	s_waitcnt lgkmcnt(0)
	ds_read2_b32 v[50:51], v41 offset0:33 offset1:41
	ds_read2_b32 v[52:53], v41 offset1:8
	ds_read2_b32 v[54:55], v41 offset0:66 offset1:74
	ds_read2_b32 v[56:57], v41 offset0:99 offset1:107
	ds_read2_b32 v[58:59], v41 offset0:132 offset1:140
	ds_read2_b32 v[60:61], v41 offset0:165 offset1:173
	ds_read2_b32 v[62:63], v41 offset0:198 offset1:206
	ds_read2_b32 v[64:65], v41 offset0:231 offset1:239
	v_or_b32_e32 v0, s2, v9
	s_movk_i32 s3, 0x180
	s_ashr_i32 s5, s4, 31
	v_mul_lo_u32 v66, v0, s3
	v_lshl_add_u64 v[38:39], s[4:5], 1, v[12:13]
	v_ashrrev_i32_e32 v67, 31, v66
	v_or_b32_e32 v0, s2, v42
	s_waitcnt lgkmcnt(6)
	v_cvt_pk_bf16_f32 v46, v52, v50
	s_waitcnt lgkmcnt(4)
	v_cvt_pk_bf16_f32 v47, v54, v56
	s_waitcnt lgkmcnt(2)
	v_cvt_pk_bf16_f32 v48, v58, v60
	s_waitcnt lgkmcnt(0)
	v_cvt_pk_bf16_f32 v49, v62, v64
	v_lshl_add_u64 v[66:67], v[66:67], 1, v[38:39]
	v_mul_lo_u32 v50, v0, s3
	global_store_dwordx4 v[66:67], v[46:49], off
	v_or_b32_e32 v0, s2, v43
	v_mul_lo_u32 v66, v0, s3
	v_cvt_pk_bf16_f32 v46, v53, v51
	v_ashrrev_i32_e32 v51, 31, v50
	v_cvt_pk_bf16_f32 v47, v55, v57
	v_cvt_pk_bf16_f32 v48, v59, v61
	v_cvt_pk_bf16_f32 v49, v63, v65
	v_lshl_add_u64 v[50:51], v[50:51], 1, v[38:39]
	global_store_dwordx4 v[50:51], v[46:49], off
	ds_read2_b32 v[50:51], v41 offset0:49 offset1:57
	ds_read2_b32 v[52:53], v41 offset0:16 offset1:24
	ds_read2_b32 v[54:55], v41 offset0:82 offset1:90
	ds_read2_b32 v[56:57], v41 offset0:115 offset1:123
	ds_read2_b32 v[58:59], v41 offset0:148 offset1:156
	ds_read2_b32 v[60:61], v41 offset0:181 offset1:189
	ds_read2_b32 v[62:63], v41 offset0:214 offset1:222
	ds_read2_b32 v[64:65], v41 offset0:247 offset1:255
	v_ashrrev_i32_e32 v67, 31, v66
	v_or_b32_e32 v0, s2, v44
	s_waitcnt lgkmcnt(6)
	v_cvt_pk_bf16_f32 v46, v52, v50
	s_waitcnt lgkmcnt(4)
	v_cvt_pk_bf16_f32 v47, v54, v56
	s_waitcnt lgkmcnt(2)
	v_cvt_pk_bf16_f32 v48, v58, v60
	s_waitcnt lgkmcnt(0)
	v_cvt_pk_bf16_f32 v49, v62, v64
	v_lshl_add_u64 v[66:67], v[66:67], 1, v[38:39]
	v_mul_lo_u32 v50, v0, s3
	global_store_dwordx4 v[66:67], v[46:49], off
	s_nop 1
	v_cvt_pk_bf16_f32 v46, v53, v51
	v_ashrrev_i32_e32 v51, 31, v50
	v_cvt_pk_bf16_f32 v47, v55, v57
	v_cvt_pk_bf16_f32 v48, v59, v61
	v_cvt_pk_bf16_f32 v49, v63, v65
	v_lshl_add_u64 v[38:39], v[50:51], 1, v[38:39]
	global_store_dwordx4 v[38:39], v[46:49], off
	s_waitcnt lgkmcnt(0)

; __device__ __forceinline__ void transpose_item(const float* __restrict__ W, int K, int N, bf16_t* __restrict__ WT, LAS float* scr, int item, int lane, bool ffn_remap = false) {
;     ...
; #pragma unroll 8
;     for (int i = 0; i < 32; ++i) { const int kk = 2 * i + (lane >> 5); scr[kk * 33 + (lane & 31)] = W[(size_t)(k0 + kk) * N + n0 + (lane & 31)]; }
.LBB0_299:
	s_lshl_b32 s13, s4, 1
	s_lshl_b32 s12, s2, 1
	v_or_b32_e32 v48, s13, v0
	v_or_b32_e32 v46, s12, v7
	v_mad_u64_u32 v[48:49], s[14:15], s34, v48, 0
	v_mad_u64_u32 v[46:47], s[14:15], s7, v46, 0
	v_lshl_add_u64 v[48:49], v[48:49], 2, v[38:39]
	v_lshl_add_u64 v[46:47], v[46:47], 2, v[38:39]
	global_load_dword v100, v[48:49], off
	global_load_dword v101, v[46:47], off
	v_or_b32_e32 v40, s12, v5
	v_or_b32_e32 v45, s13, v4
	v_mad_u64_u32 v[116:117], s[14:15], v45, s37, v[8:9]
	v_mad_u64_u32 v[118:119], s[14:15], v40, s37, v[8:9]
	s_add_i32 s15, s13, 4
	s_add_i32 s14, s12, 4
	v_or_b32_e32 v40, s14, v5
	v_or_b32_e32 v45, s15, v4
	s_add_i32 s4, s4, 16
	s_add_i32 s2, s2, 16
	s_add_i32 s5, s5, -16
	v_or_b32_e32 v48, s15, v0
	v_or_b32_e32 v46, s14, v7
	v_mad_u64_u32 v[48:49], s[14:15], s34, v48, 0
	v_mad_u64_u32 v[46:47], s[14:15], s7, v46, 0
	v_lshl_add_u64 v[48:49], v[48:49], 2, v[38:39]
	v_lshl_add_u64 v[46:47], v[46:47], 2, v[38:39]
	global_load_dword v102, v[48:49], off
	global_load_dword v103, v[46:47], off
	v_mad_u64_u32 v[120:121], s[14:15], v45, s37, v[8:9]
	v_mad_u64_u32 v[122:123], s[14:15], v40, s37, v[8:9]
	s_add_i32 s15, s13, 8
	s_add_i32 s14, s12, 8
	v_or_b32_e32 v40, s14, v5
	v_or_b32_e32 v45, s15, v4
	v_or_b32_e32 v48, s15, v0
	v_or_b32_e32 v46, s14, v7
	v_mad_u64_u32 v[48:49], s[14:15], s34, v48, 0
	v_mad_u64_u32 v[46:47], s[14:15], s7, v46, 0
	v_lshl_add_u64 v[48:49], v[48:49], 2, v[38:39]
	v_lshl_add_u64 v[46:47], v[46:47], 2, v[38:39]
	global_load_dword v104, v[48:49], off
	global_load_dword v105, v[46:47], off
	v_mad_u64_u32 v[124:125], s[14:15], v45, s37, v[8:9]
	v_mad_u64_u32 v[126:127], s[14:15], v40, s37, v[8:9]
	s_add_i32 s15, s13, 12
	s_add_i32 s14, s12, 12
	v_or_b32_e32 v40, s14, v5
	v_or_b32_e32 v45, s15, v4
	v_or_b32_e32 v48, s15, v0
	v_or_b32_e32 v46, s14, v7
	v_mad_u64_u32 v[48:49], s[14:15], s34, v48, 0
	v_mad_u64_u32 v[46:47], s[14:15], s7, v46, 0
	v_lshl_add_u64 v[48:49], v[48:49], 2, v[38:39]
	v_lshl_add_u64 v[46:47], v[46:47], 2, v[38:39]
	global_load_dword v106, v[48:49], off
	global_load_dword v107, v[46:47], off
	v_mad_u64_u32 v[128:129], s[14:15], v45, s37, v[8:9]
	v_mad_u64_u32 v[130:131], s[14:15], v40, s37, v[8:9]
	s_add_i32 s15, s13, 16
	s_add_i32 s14, s12, 16
	v_or_b32_e32 v40, s14, v5
	v_or_b32_e32 v45, s15, v4
	v_or_b32_e32 v48, s15, v0
	v_or_b32_e32 v46, s14, v7
	v_mad_u64_u32 v[48:49], s[14:15], s34, v48, 0
	v_mad_u64_u32 v[46:47], s[14:15], s7, v46, 0
	v_lshl_add_u64 v[48:49], v[48:49], 2, v[38:39]
	v_lshl_add_u64 v[46:47], v[46:47], 2, v[38:39]
	global_load_dword v108, v[48:49], off
	global_load_dword v109, v[46:47], off
	v_mad_u64_u32 v[132:133], s[14:15], v45, s37, v[8:9]
	v_mad_u64_u32 v[134:135], s[14:15], v40, s37, v[8:9]
	s_add_i32 s15, s13, 20
	s_add_i32 s14, s12, 20
	v_or_b32_e32 v40, s14, v5
	v_or_b32_e32 v45, s15, v4
	v_or_b32_e32 v48, s15, v0
	v_or_b32_e32 v46, s14, v7
	v_mad_u64_u32 v[48:49], s[14:15], s34, v48, 0
	v_mad_u64_u32 v[46:47], s[14:15], s7, v46, 0
	v_lshl_add_u64 v[48:49], v[48:49], 2, v[38:39]
	v_lshl_add_u64 v[46:47], v[46:47], 2, v[38:39]
	global_load_dword v110, v[48:49], off
	global_load_dword v111, v[46:47], off
	v_mad_u64_u32 v[136:137], s[14:15], v45, s37, v[8:9]
	v_mad_u64_u32 v[138:139], s[14:15], v40, s37, v[8:9]
	s_add_i32 s15, s13, 24
	s_add_i32 s14, s12, 24
	v_or_b32_e32 v40, s14, v5
	v_or_b32_e32 v45, s15, v4
	s_add_i32 s13, s13, 28
	s_add_i32 s12, s12, 28
	s_cmp_lg_u32 s5, 0
	v_or_b32_e32 v48, s15, v0
	v_or_b32_e32 v46, s14, v7
	v_mad_u64_u32 v[48:49], s[14:15], s34, v48, 0
	v_mad_u64_u32 v[46:47], s[14:15], s7, v46, 0
	v_lshl_add_u64 v[48:49], v[48:49], 2, v[38:39]
	v_lshl_add_u64 v[46:47], v[46:47], 2, v[38:39]
	global_load_dword v112, v[48:49], off
	global_load_dword v113, v[46:47], off
	v_mad_u64_u32 v[140:141], s[14:15], v45, s37, v[8:9]
	v_mad_u64_u32 v[142:143], s[14:15], v40, s37, v[8:9]
	v_or_b32_e32 v40, s12, v5
	v_or_b32_e32 v45, s13, v4
	v_or_b32_e32 v48, s13, v0
	v_or_b32_e32 v46, s12, v7
	v_mad_u64_u32 v[48:49], s[12:13], s34, v48, 0
	v_mad_u64_u32 v[46:47], s[12:13], s7, v46, 0
	v_lshl_add_u64 v[48:49], v[48:49], 2, v[38:39]
	v_lshl_add_u64 v[46:47], v[46:47], 2, v[38:39]
	global_load_dword v114, v[48:49], off
	global_load_dword v115, v[46:47], off
	v_mad_u64_u32 v[144:145], s[12:13], v45, s37, v[8:9]
	v_mad_u64_u32 v[146:147], s[12:13], v40, s37, v[8:9]
	s_waitcnt vmcnt(15)
	ds_write_b32 v116, v100
	s_waitcnt vmcnt(14)
	ds_write_b32 v118, v101
	s_waitcnt vmcnt(13)
	ds_write_b32 v120, v102
	s_waitcnt vmcnt(12)
	ds_write_b32 v122, v103
	s_waitcnt vmcnt(11)
	ds_write_b32 v124, v104
	s_waitcnt vmcnt(10)
	ds_write_b32 v126, v105
	s_waitcnt vmcnt(9)
	ds_write_b32 v128, v106
	s_waitcnt vmcnt(8)
	ds_write_b32 v130, v107
	s_waitcnt vmcnt(7)
	ds_write_b32 v132, v108
	s_waitcnt vmcnt(6)
	ds_write_b32 v134, v109
	s_waitcnt vmcnt(5)
	ds_write_b32 v136, v110
	s_waitcnt vmcnt(4)
	ds_write_b32 v138, v111
	s_waitcnt vmcnt(3)
	ds_write_b32 v140, v112
	s_waitcnt vmcnt(2)
	ds_write_b32 v142, v113
	s_waitcnt vmcnt(1)
	ds_write_b32 v144, v114
	s_waitcnt vmcnt(0)
	ds_write_b32 v146, v115
	s_cbranch_scc1 .LBB0_299
; #define LAS __attribute__((address_space(3)))
; __device__ __forceinline__ unsigned pk2(float lo, float hi) { f32x2_t v = {lo, hi}; bf16x2_t b = __builtin_convertvector(v, bf16x2_t); return __builtin_bit_cast(unsigned, b); }
; __device__ __forceinline__ void transpose_item(const float* __restrict__ W, int K, int N, bf16_t* __restrict__ WT, LAS float* scr, int item, int lane, bool ffn_remap = false) {
;     ...
;     asm volatile("s_waitcnt lgkmcnt(0)" ::: "memory");
;     const int c = lane & 7;
; #pragma unroll
;     for (int j = 0; j < 4; ++j) { const int n = (lane >> 3) + 8 * j; const LAS float* s = scr + (8 * c) * 33 + n;
;         u32x4 o; o.x = pk2(s[0 * 33], s[1 * 33]); o.y = pk2(s[2 * 33], s[3 * 33]); o.z = pk2(s[4 * 33], s[5 * 33]); o.w = pk2(s[6 * 33], s[7 * 33]);
;         *(u32x4*)(WT + (size_t)(d0 + n) * K + k0 + 8 * c) = o; }
;     asm volatile("s_waitcnt lgkmcnt(0)" ::: "memory");
	s_waitcnt lgkmcnt(0)
	ds_read2_b32 v[50:51], v41 offset0:33 offset1:41
	ds_read2_b32 v[52:53], v41 offset1:8
	ds_read2_b32 v[54:55], v41 offset0:66 offset1:74
	ds_read2_b32 v[56:57], v41 offset0:99 offset1:107
	ds_read2_b32 v[58:59], v41 offset0:132 offset1:140
	ds_read2_b32 v[60:61], v41 offset0:165 offset1:173
	ds_read2_b32 v[62:63], v41 offset0:198 offset1:206
	ds_read2_b32 v[64:65], v41 offset0:231 offset1:239
	s_lshl_b32 s2, s3, 1
	s_mov_b32 s3, s77
	v_or_b32_e32 v0, s76, v9
	v_lshl_add_u64 v[38:39], v[16:17], 0, s[2:3]
	v_lshlrev_b32_e32 v0, 11, v0
	v_lshl_add_u64 v[66:67], v[38:39], 0, v[0:1]
	v_or_b32_e32 v0, s76, v42
	s_waitcnt lgkmcnt(6)
	v_cvt_pk_bf16_f32 v46, v52, v50
	s_waitcnt lgkmcnt(4)
	v_cvt_pk_bf16_f32 v47, v54, v56
	s_waitcnt lgkmcnt(2)
	v_cvt_pk_bf16_f32 v48, v58, v60
	s_waitcnt lgkmcnt(0)
	v_cvt_pk_bf16_f32 v49, v62, v64
	v_lshlrev_b32_e32 v0, 11, v0
	global_store_dwordx4 v[66:67], v[46:49], off
	s_nop 1
	v_cvt_pk_bf16_f32 v46, v53, v51
	v_cvt_pk_bf16_f32 v47, v55, v57
	v_cvt_pk_bf16_f32 v48, v59, v61
	v_cvt_pk_bf16_f32 v49, v63, v65
	v_lshl_add_u64 v[50:51], v[38:39], 0, v[0:1]
	global_store_dwordx4 v[50:51], v[46:49], off
	ds_read2_b32 v[50:51], v41 offset0:49 offset1:57
	ds_read2_b32 v[52:53], v41 offset0:16 offset1:24
	ds_read2_b32 v[54:55], v41 offset0:82 offset1:90
	ds_read2_b32 v[56:57], v41 offset0:115 offset1:123
	ds_read2_b32 v[58:59], v41 offset0:148 offset1:156
	ds_read2_b32 v[60:61], v41 offset0:181 offset1:189
	ds_read2_b32 v[62:63], v41 offset0:214 offset1:222
	ds_read2_b32 v[64:65], v41 offset0:247 offset1:255
	v_or_b32_e32 v0, s76, v43
	v_lshlrev_b32_e32 v0, 11, v0
	v_lshl_add_u64 v[66:67], v[38:39], 0, v[0:1]
	v_or_b32_e32 v0, s76, v44
	s_waitcnt lgkmcnt(6)
	v_cvt_pk_bf16_f32 v46, v52, v50
	s_waitcnt lgkmcnt(4)
	v_cvt_pk_bf16_f32 v47, v54, v56
	s_waitcnt lgkmcnt(2)
	v_cvt_pk_bf16_f32 v48, v58, v60
	s_waitcnt lgkmcnt(0)
	v_cvt_pk_bf16_f32 v49, v62, v64
	v_lshlrev_b32_e32 v0, 11, v0
	global_store_dwordx4 v[66:67], v[46:49], off
	v_lshl_add_u64 v[38:39], v[38:39], 0, v[0:1]
	s_nop 0
	v_cvt_pk_bf16_f32 v46, v53, v51
	v_cvt_pk_bf16_f32 v47, v55, v57
	v_cvt_pk_bf16_f32 v48, v59, v61
	v_cvt_pk_bf16_f32 v49, v63, v65
	global_store_dwordx4 v[38:39], v[46:49], off
	s_waitcnt lgkmcnt(0)

; __device__ __forceinline__ void transpose_item(const float* __restrict__ W, int K, int N, bf16_t* __restrict__ WT, LAS float* scr, int item, int lane, bool ffn_remap = false) {
;     ...
; #pragma unroll 8
;     for (int i = 0; i < 32; ++i) { const int kk = 2 * i + (lane >> 5); scr[kk * 33 + (lane & 31)] = W[(size_t)(k0 + kk) * N + n0 + (lane & 31)]; }
.LBB0_304:
	s_lshl_b32 s14, s5, 1
	s_lshl_b32 s13, s3, 1
	v_or_b32_e32 v0, s14, v40
	v_or_b32_e32 v46, s13, v7
	v_mov_b32_e32 v47, v1
	v_lshlrev_b64 v[48:49], 12, v[0:1]
	v_lshlrev_b64 v[46:47], 12, v[46:47]
	v_lshl_add_u64 v[48:49], v[38:39], 0, v[48:49]
	v_lshl_add_u64 v[46:47], v[38:39], 0, v[46:47]
	global_load_dword v100, v[48:49], off
	global_load_dword v101, v[46:47], off
	v_or_b32_e32 v45, s13, v5
	v_or_b32_e32 v50, s14, v4
	v_mad_u64_u32 v[116:117], s[16:17], v50, s37, v[8:9]
	v_mad_u64_u32 v[118:119], s[16:17], v45, s37, v[8:9]
	s_add_i32 s16, s14, 4
	s_add_i32 s15, s13, 4
	v_mov_b32_e32 v47, v1
	v_or_b32_e32 v45, s15, v5
	v_or_b32_e32 v50, s16, v4
	s_add_i32 s5, s5, 16
	s_add_i32 s3, s3, 16
	s_add_i32 s12, s12, -16
	v_or_b32_e32 v0, s16, v40
	v_or_b32_e32 v46, s15, v7
	v_lshlrev_b64 v[48:49], 12, v[0:1]
	v_lshlrev_b64 v[46:47], 12, v[46:47]
	v_lshl_add_u64 v[48:49], v[38:39], 0, v[48:49]
	v_lshl_add_u64 v[46:47], v[38:39], 0, v[46:47]
	global_load_dword v102, v[48:49], off
	global_load_dword v103, v[46:47], off
	v_mad_u64_u32 v[120:121], s[16:17], v50, s37, v[8:9]
	v_mad_u64_u32 v[122:123], s[16:17], v45, s37, v[8:9]
	s_add_i32 s16, s14, 8
	s_add_i32 s15, s13, 8
	v_mov_b32_e32 v47, v1
	v_or_b32_e32 v45, s15, v5
	v_or_b32_e32 v50, s16, v4
	v_or_b32_e32 v0, s16, v40
	v_or_b32_e32 v46, s15, v7
	v_lshlrev_b64 v[48:49], 12, v[0:1]
	v_lshlrev_b64 v[46:47], 12, v[46:47]
	v_lshl_add_u64 v[48:49], v[38:39], 0, v[48:49]
	v_lshl_add_u64 v[46:47], v[38:39], 0, v[46:47]
	global_load_dword v104, v[48:49], off
	global_load_dword v105, v[46:47], off
	v_mad_u64_u32 v[124:125], s[16:17], v50, s37, v[8:9]
	v_mad_u64_u32 v[126:127], s[16:17], v45, s37, v[8:9]
	s_add_i32 s16, s14, 12
	s_add_i32 s15, s13, 12
	v_mov_b32_e32 v47, v1
	v_or_b32_e32 v45, s15, v5
	v_or_b32_e32 v50, s16, v4
	v_or_b32_e32 v0, s16, v40
	v_or_b32_e32 v46, s15, v7
	v_lshlrev_b64 v[48:49], 12, v[0:1]
	v_lshlrev_b64 v[46:47], 12, v[46:47]
	v_lshl_add_u64 v[48:49], v[38:39], 0, v[48:49]
	v_lshl_add_u64 v[46:47], v[38:39], 0, v[46:47]
	global_load_dword v106, v[48:49], off
	global_load_dword v107, v[46:47], off
	v_mad_u64_u32 v[128:129], s[16:17], v50, s37, v[8:9]
	v_mad_u64_u32 v[130:131], s[16:17], v45, s37, v[8:9]
	s_add_i32 s16, s14, 16
	s_add_i32 s15, s13, 16
	v_mov_b32_e32 v47, v1
	v_or_b32_e32 v45, s15, v5
	v_or_b32_e32 v50, s16, v4
	v_or_b32_e32 v0, s16, v40
	v_or_b32_e32 v46, s15, v7
	v_lshlrev_b64 v[48:49], 12, v[0:1]
	v_lshlrev_b64 v[46:47], 12, v[46:47]
	v_lshl_add_u64 v[48:49], v[38:39], 0, v[48:49]
	v_lshl_add_u64 v[46:47], v[38:39], 0, v[46:47]
	global_load_dword v108, v[48:49], off
	global_load_dword v109, v[46:47], off
	v_mad_u64_u32 v[132:133], s[16:17], v50, s37, v[8:9]
	v_mad_u64_u32 v[134:135], s[16:17], v45, s37, v[8:9]
	s_add_i32 s16, s14, 20
	s_add_i32 s15, s13, 20
	v_mov_b32_e32 v47, v1
	v_or_b32_e32 v45, s15, v5
	v_or_b32_e32 v50, s16, v4
	v_or_b32_e32 v0, s16, v40
	v_or_b32_e32 v46, s15, v7
	v_lshlrev_b64 v[48:49], 12, v[0:1]
	v_lshlrev_b64 v[46:47], 12, v[46:47]
	v_lshl_add_u64 v[48:49], v[38:39], 0, v[48:49]
	v_lshl_add_u64 v[46:47], v[38:39], 0, v[46:47]
	global_load_dword v110, v[48:49], off
	global_load_dword v111, v[46:47], off
	v_mad_u64_u32 v[136:137], s[16:17], v50, s37, v[8:9]
	v_mad_u64_u32 v[138:139], s[16:17], v45, s37, v[8:9]
	s_add_i32 s16, s14, 24
	s_add_i32 s15, s13, 24
	v_mov_b32_e32 v47, v1
	v_or_b32_e32 v50, s16, v4
	v_or_b32_e32 v45, s15, v5
	s_add_i32 s14, s14, 28
	s_add_i32 s13, s13, 28
	s_cmp_lg_u32 s12, 0
	v_or_b32_e32 v0, s16, v40
	v_or_b32_e32 v46, s15, v7
	v_lshlrev_b64 v[48:49], 12, v[0:1]
	v_lshlrev_b64 v[46:47], 12, v[46:47]
	v_lshl_add_u64 v[48:49], v[38:39], 0, v[48:49]
	v_lshl_add_u64 v[46:47], v[38:39], 0, v[46:47]
	global_load_dword v112, v[48:49], off
	global_load_dword v113, v[46:47], off
	v_mad_u64_u32 v[140:141], s[16:17], v50, s37, v[8:9]
	v_mad_u64_u32 v[142:143], s[16:17], v45, s37, v[8:9]
	v_mov_b32_e32 v47, v1
	v_or_b32_e32 v50, s14, v4
	v_or_b32_e32 v45, s13, v5
	v_or_b32_e32 v0, s14, v40
	v_or_b32_e32 v46, s13, v7
	v_lshlrev_b64 v[48:49], 12, v[0:1]
	v_lshlrev_b64 v[46:47], 12, v[46:47]
	v_lshl_add_u64 v[48:49], v[38:39], 0, v[48:49]
	v_lshl_add_u64 v[46:47], v[38:39], 0, v[46:47]
	global_load_dword v114, v[48:49], off
	global_load_dword v115, v[46:47], off
	v_mad_u64_u32 v[144:145], s[14:15], v50, s37, v[8:9]
	v_mad_u64_u32 v[146:147], s[14:15], v45, s37, v[8:9]
	s_waitcnt vmcnt(15)
	ds_write_b32 v116, v100
	s_waitcnt vmcnt(14)
	ds_write_b32 v118, v101
	s_waitcnt vmcnt(13)
	ds_write_b32 v120, v102
	s_waitcnt vmcnt(12)
	ds_write_b32 v122, v103
	s_waitcnt vmcnt(11)
	ds_write_b32 v124, v104
	s_waitcnt vmcnt(10)
	ds_write_b32 v126, v105
	s_waitcnt vmcnt(9)
	ds_write_b32 v128, v106
	s_waitcnt vmcnt(8)
	ds_write_b32 v130, v107
	s_waitcnt vmcnt(7)
	ds_write_b32 v132, v108
	s_waitcnt vmcnt(6)
	ds_write_b32 v134, v109
	s_waitcnt vmcnt(5)
	ds_write_b32 v136, v110
	s_waitcnt vmcnt(4)
	ds_write_b32 v138, v111
	s_waitcnt vmcnt(3)
	ds_write_b32 v140, v112
	s_waitcnt vmcnt(2)
	ds_write_b32 v142, v113
	s_waitcnt vmcnt(1)
	ds_write_b32 v144, v114
	s_waitcnt vmcnt(0)
	ds_write_b32 v146, v115
	s_cbranch_scc1 .LBB0_304
; #define LAS __attribute__((address_space(3)))
; __device__ __forceinline__ unsigned pk2(float lo, float hi) { f32x2_t v = {lo, hi}; bf16x2_t b = __builtin_convertvector(v, bf16x2_t); return __builtin_bit_cast(unsigned, b); }
; __device__ __forceinline__ void transpose_item(const float* __restrict__ W, int K, int N, bf16_t* __restrict__ WT, LAS float* scr, int item, int lane, bool ffn_remap = false) {
;     ...
;     asm volatile("s_waitcnt lgkmcnt(0)" ::: "memory");
;     const int c = lane & 7;
; #pragma unroll
;     for (int j = 0; j < 4; ++j) { const int n = (lane >> 3) + 8 * j; const LAS float* s = scr + (8 * c) * 33 + n;
;         u32x4 o; o.x = pk2(s[0 * 33], s[1 * 33]); o.y = pk2(s[2 * 33], s[3 * 33]); o.z = pk2(s[4 * 33], s[5 * 33]); o.w = pk2(s[6 * 33], s[7 * 33]);
;         *(u32x4*)(WT + (size_t)(d0 + n) * K + k0 + 8 * c) = o; }
;     asm volatile("s_waitcnt lgkmcnt(0)" ::: "memory");
	s_waitcnt lgkmcnt(0)
	ds_read2_b32 v[50:51], v41 offset0:33 offset1:41
	ds_read2_b32 v[52:53], v41 offset1:8
	ds_read2_b32 v[54:55], v41 offset0:66 offset1:74
	ds_read2_b32 v[56:57], v41 offset0:99 offset1:107
	ds_read2_b32 v[58:59], v41 offset0:132 offset1:140
	ds_read2_b32 v[60:61], v41 offset0:165 offset1:173
	ds_read2_b32 v[62:63], v41 offset0:198 offset1:206
	ds_read2_b32 v[64:65], v41 offset0:231 offset1:239
	s_lshl_b32 s76, s4, 1
	v_or_b32_e32 v0, s2, v9
	v_lshl_add_u64 v[38:39], v[20:21], 0, s[76:77]
	v_lshlrev_b32_e32 v0, 11, v0
	v_lshl_add_u64 v[66:67], v[38:39], 0, v[0:1]
	v_or_b32_e32 v0, s2, v42
	s_waitcnt lgkmcnt(6)
	v_cvt_pk_bf16_f32 v46, v52, v50
	s_waitcnt lgkmcnt(4)
	v_cvt_pk_bf16_f32 v47, v54, v56
	s_waitcnt lgkmcnt(2)
	v_cvt_pk_bf16_f32 v48, v58, v60
	s_waitcnt lgkmcnt(0)
	v_cvt_pk_bf16_f32 v49, v62, v64
	v_lshlrev_b32_e32 v0, 11, v0
	global_store_dwordx4 v[66:67], v[46:49], off
	s_nop 1
	v_cvt_pk_bf16_f32 v46, v53, v51
	v_cvt_pk_bf16_f32 v47, v55, v57
	v_cvt_pk_bf16_f32 v48, v59, v61
	v_cvt_pk_bf16_f32 v49, v63, v65
	v_lshl_add_u64 v[50:51], v[38:39], 0, v[0:1]
	global_store_dwordx4 v[50:51], v[46:49], off
	ds_read2_b32 v[50:51], v41 offset0:49 offset1:57
	ds_read2_b32 v[52:53], v41 offset0:16 offset1:24
	ds_read2_b32 v[54:55], v41 offset0:82 offset1:90
	ds_read2_b32 v[56:57], v41 offset0:115 offset1:123
	ds_read2_b32 v[58:59], v41 offset0:148 offset1:156
	ds_read2_b32 v[60:61], v41 offset0:181 offset1:189
	ds_read2_b32 v[62:63], v41 offset0:214 offset1:222
	ds_read2_b32 v[64:65], v41 offset0:247 offset1:255
	v_or_b32_e32 v0, s2, v43
	v_lshlrev_b32_e32 v0, 11, v0
	v_lshl_add_u64 v[66:67], v[38:39], 0, v[0:1]
	v_or_b32_e32 v0, s2, v44
	s_waitcnt lgkmcnt(6)
	v_cvt_pk_bf16_f32 v46, v52, v50
	s_waitcnt lgkmcnt(4)
	v_cvt_pk_bf16_f32 v47, v54, v56
	s_waitcnt lgkmcnt(2)
	v_cvt_pk_bf16_f32 v48, v58, v60
	s_waitcnt lgkmcnt(0)
	v_cvt_pk_bf16_f32 v49, v62, v64
	v_lshlrev_b32_e32 v0, 11, v0
	global_store_dwordx4 v[66:67], v[46:49], off
	v_lshl_add_u64 v[38:39], v[38:39], 0, v[0:1]
	s_nop 0
	v_cvt_pk_bf16_f32 v46, v53, v51
	v_cvt_pk_bf16_f32 v47, v55, v57
	v_cvt_pk_bf16_f32 v48, v59, v61
	v_cvt_pk_bf16_f32 v49, v63, v65
	global_store_dwordx4 v[38:39], v[46:49], off
	s_waitcnt lgkmcnt(0)

; __device__ __forceinline__ void transpose_item(const float* __restrict__ W, int K, int N, bf16_t* __restrict__ WT, LAS float* scr, int item, int lane, bool ffn_remap = false) {
;     ...
; #pragma unroll 8
;     for (int i = 0; i < 32; ++i) { const int kk = 2 * i + (lane >> 5); scr[kk * 33 + (lane & 31)] = W[(size_t)(k0 + kk) * N + n0 + (lane & 31)]; }
.LBB0_309:
	s_lshl_b32 s14, s5, 1
	s_lshl_b32 s13, s4, 1
	v_or_b32_e32 v0, s14, v40
	v_or_b32_e32 v46, s13, v7
	v_mov_b32_e32 v47, v1
	v_lshlrev_b64 v[48:49], 12, v[0:1]
	v_lshlrev_b64 v[46:47], 12, v[46:47]
	v_lshl_add_u64 v[48:49], v[38:39], 0, v[48:49]
	v_lshl_add_u64 v[46:47], v[38:39], 0, v[46:47]
	global_load_dword v100, v[48:49], off
	global_load_dword v101, v[46:47], off
	v_or_b32_e32 v45, s13, v5
	v_or_b32_e32 v50, s14, v4
	v_mad_u64_u32 v[116:117], s[16:17], v50, s37, v[8:9]
	v_mad_u64_u32 v[118:119], s[16:17], v45, s37, v[8:9]
	s_add_i32 s16, s14, 4
	s_add_i32 s15, s13, 4
	v_mov_b32_e32 v47, v1
	v_or_b32_e32 v45, s15, v5
	v_or_b32_e32 v50, s16, v4
	s_add_i32 s5, s5, 16
	s_add_i32 s4, s4, 16
	s_add_i32 s12, s12, -16
	v_or_b32_e32 v0, s16, v40
	v_or_b32_e32 v46, s15, v7
	v_lshlrev_b64 v[48:49], 12, v[0:1]
	v_lshlrev_b64 v[46:47], 12, v[46:47]
	v_lshl_add_u64 v[48:49], v[38:39], 0, v[48:49]
	v_lshl_add_u64 v[46:47], v[38:39], 0, v[46:47]
	global_load_dword v102, v[48:49], off
	global_load_dword v103, v[46:47], off
	v_mad_u64_u32 v[120:121], s[16:17], v50, s37, v[8:9]
	v_mad_u64_u32 v[122:123], s[16:17], v45, s37, v[8:9]
	s_add_i32 s16, s14, 8
	s_add_i32 s15, s13, 8
	v_mov_b32_e32 v47, v1
	v_or_b32_e32 v45, s15, v5
	v_or_b32_e32 v50, s16, v4
	v_or_b32_e32 v0, s16, v40
	v_or_b32_e32 v46, s15, v7
	v_lshlrev_b64 v[48:49], 12, v[0:1]
	v_lshlrev_b64 v[46:47], 12, v[46:47]
	v_lshl_add_u64 v[48:49], v[38:39], 0, v[48:49]
	v_lshl_add_u64 v[46:47], v[38:39], 0, v[46:47]
	global_load_dword v104, v[48:49], off
	global_load_dword v105, v[46:47], off
	v_mad_u64_u32 v[124:125], s[16:17], v50, s37, v[8:9]
	v_mad_u64_u32 v[126:127], s[16:17], v45, s37, v[8:9]
	s_add_i32 s16, s14, 12
	s_add_i32 s15, s13, 12
	v_mov_b32_e32 v47, v1
	v_or_b32_e32 v45, s15, v5
	v_or_b32_e32 v50, s16, v4
	v_or_b32_e32 v0, s16, v40
	v_or_b32_e32 v46, s15, v7
	v_lshlrev_b64 v[48:49], 12, v[0:1]
	v_lshlrev_b64 v[46:47], 12, v[46:47]
	v_lshl_add_u64 v[48:49], v[38:39], 0, v[48:49]
	v_lshl_add_u64 v[46:47], v[38:39], 0, v[46:47]
	global_load_dword v106, v[48:49], off
	global_load_dword v107, v[46:47], off
	v_mad_u64_u32 v[128:129], s[16:17], v50, s37, v[8:9]
	v_mad_u64_u32 v[130:131], s[16:17], v45, s37, v[8:9]
	s_add_i32 s16, s14, 16
	s_add_i32 s15, s13, 16
	v_mov_b32_e32 v47, v1
	v_or_b32_e32 v45, s15, v5
	v_or_b32_e32 v50, s16, v4
	v_or_b32_e32 v0, s16, v40
	v_or_b32_e32 v46, s15, v7
	v_lshlrev_b64 v[48:49], 12, v[0:1]
	v_lshlrev_b64 v[46:47], 12, v[46:47]
	v_lshl_add_u64 v[48:49], v[38:39], 0, v[48:49]
	v_lshl_add_u64 v[46:47], v[38:39], 0, v[46:47]
	global_load_dword v108, v[48:49], off
	global_load_dword v109, v[46:47], off
	v_mad_u64_u32 v[132:133], s[16:17], v50, s37, v[8:9]
	v_mad_u64_u32 v[134:135], s[16:17], v45, s37, v[8:9]
	s_add_i32 s16, s14, 20
	s_add_i32 s15, s13, 20
	v_mov_b32_e32 v47, v1
	v_or_b32_e32 v45, s15, v5
	v_or_b32_e32 v50, s16, v4
	v_or_b32_e32 v0, s16, v40
	v_or_b32_e32 v46, s15, v7
	v_lshlrev_b64 v[48:49], 12, v[0:1]
	v_lshlrev_b64 v[46:47], 12, v[46:47]
	v_lshl_add_u64 v[48:49], v[38:39], 0, v[48:49]
	v_lshl_add_u64 v[46:47], v[38:39], 0, v[46:47]
	global_load_dword v110, v[48:49], off
	global_load_dword v111, v[46:47], off
	v_mad_u64_u32 v[136:137], s[16:17], v50, s37, v[8:9]
	v_mad_u64_u32 v[138:139], s[16:17], v45, s37, v[8:9]
	s_add_i32 s16, s14, 24
	s_add_i32 s15, s13, 24
	v_mov_b32_e32 v47, v1
	v_or_b32_e32 v50, s16, v4
	v_or_b32_e32 v45, s15, v5
	s_add_i32 s14, s14, 28
	s_add_i32 s13, s13, 28
	s_cmp_lg_u32 s12, 0
	v_or_b32_e32 v0, s16, v40
	v_or_b32_e32 v46, s15, v7
	v_lshlrev_b64 v[48:49], 12, v[0:1]
	v_lshlrev_b64 v[46:47], 12, v[46:47]
	v_lshl_add_u64 v[48:49], v[38:39], 0, v[48:49]
	v_lshl_add_u64 v[46:47], v[38:39], 0, v[46:47]
	global_load_dword v112, v[48:49], off
	global_load_dword v113, v[46:47], off
	v_mad_u64_u32 v[140:141], s[16:17], v50, s37, v[8:9]
	v_mad_u64_u32 v[142:143], s[16:17], v45, s37, v[8:9]
	v_mov_b32_e32 v47, v1
	v_or_b32_e32 v50, s14, v4
	v_or_b32_e32 v45, s13, v5
	v_or_b32_e32 v0, s14, v40
	v_or_b32_e32 v46, s13, v7
	v_lshlrev_b64 v[48:49], 12, v[0:1]
	v_lshlrev_b64 v[46:47], 12, v[46:47]
	v_lshl_add_u64 v[48:49], v[38:39], 0, v[48:49]
	v_lshl_add_u64 v[46:47], v[38:39], 0, v[46:47]
	global_load_dword v114, v[48:49], off
	global_load_dword v115, v[46:47], off
	v_mad_u64_u32 v[144:145], s[14:15], v50, s37, v[8:9]
	v_mad_u64_u32 v[146:147], s[14:15], v45, s37, v[8:9]
	s_waitcnt vmcnt(15)
	ds_write_b32 v116, v100
	s_waitcnt vmcnt(14)
	ds_write_b32 v118, v101
	s_waitcnt vmcnt(13)
	ds_write_b32 v120, v102
	s_waitcnt vmcnt(12)
	ds_write_b32 v122, v103
	s_waitcnt vmcnt(11)
	ds_write_b32 v124, v104
	s_waitcnt vmcnt(10)
	ds_write_b32 v126, v105
	s_waitcnt vmcnt(9)
	ds_write_b32 v128, v106
	s_waitcnt vmcnt(8)
	ds_write_b32 v130, v107
	s_waitcnt vmcnt(7)
	ds_write_b32 v132, v108
	s_waitcnt vmcnt(6)
	ds_write_b32 v134, v109
	s_waitcnt vmcnt(5)
	ds_write_b32 v136, v110
	s_waitcnt vmcnt(4)
	ds_write_b32 v138, v111
	s_waitcnt vmcnt(3)
	ds_write_b32 v140, v112
	s_waitcnt vmcnt(2)
	ds_write_b32 v142, v113
	s_waitcnt vmcnt(1)
	ds_write_b32 v144, v114
	s_waitcnt vmcnt(0)
	ds_write_b32 v146, v115
	s_cbranch_scc1 .LBB0_309
; #define LAS __attribute__((address_space(3)))
; __device__ __forceinline__ unsigned pk2(float lo, float hi) { f32x2_t v = {lo, hi}; bf16x2_t b = __builtin_convertvector(v, bf16x2_t); return __builtin_bit_cast(unsigned, b); }
; __device__ __forceinline__ void transpose_item(const float* __restrict__ W, int K, int N, bf16_t* __restrict__ WT, LAS float* scr, int item, int lane, bool ffn_remap = false) {
;     ...
;     asm volatile("s_waitcnt lgkmcnt(0)" ::: "memory");
;     const int c = lane & 7;
; #pragma unroll
;     for (int j = 0; j < 4; ++j) { const int n = (lane >> 3) + 8 * j; const LAS float* s = scr + (8 * c) * 33 + n;
;         u32x4 o; o.x = pk2(s[0 * 33], s[1 * 33]); o.y = pk2(s[2 * 33], s[3 * 33]); o.z = pk2(s[4 * 33], s[5 * 33]); o.w = pk2(s[6 * 33], s[7 * 33]);
;         *(u32x4*)(WT + (size_t)(d0 + n) * K + k0 + 8 * c) = o; }
;     asm volatile("s_waitcnt lgkmcnt(0)" ::: "memory");
	s_waitcnt lgkmcnt(0)
	ds_read2_b32 v[50:51], v41 offset0:33 offset1:41
	ds_read2_b32 v[52:53], v41 offset1:8
	ds_read2_b32 v[54:55], v41 offset0:66 offset1:74
	ds_read2_b32 v[56:57], v41 offset0:99 offset1:107
	ds_read2_b32 v[58:59], v41 offset0:132 offset1:140
	ds_read2_b32 v[60:61], v41 offset0:165 offset1:173
	ds_read2_b32 v[62:63], v41 offset0:198 offset1:206
	ds_read2_b32 v[64:65], v41 offset0:231 offset1:239
	s_lshl_b32 s76, s3, 1
	v_or_b32_e32 v0, s2, v9
	v_lshl_add_u64 v[38:39], v[24:25], 0, s[76:77]
	v_lshlrev_b32_e32 v0, 9, v0
	v_lshl_add_u64 v[66:67], v[38:39], 0, v[0:1]
	v_or_b32_e32 v0, s2, v42
	s_waitcnt lgkmcnt(6)
	v_cvt_pk_bf16_f32 v46, v52, v50
	s_waitcnt lgkmcnt(4)
	v_cvt_pk_bf16_f32 v47, v54, v56
	s_waitcnt lgkmcnt(2)
	v_cvt_pk_bf16_f32 v48, v58, v60
	s_waitcnt lgkmcnt(0)
	v_cvt_pk_bf16_f32 v49, v62, v64
	v_lshlrev_b32_e32 v0, 9, v0
	global_store_dwordx4 v[66:67], v[46:49], off
	s_nop 1
	v_cvt_pk_bf16_f32 v46, v53, v51
	v_cvt_pk_bf16_f32 v47, v55, v57
	v_cvt_pk_bf16_f32 v48, v59, v61
	v_cvt_pk_bf16_f32 v49, v63, v65
	v_lshl_add_u64 v[50:51], v[38:39], 0, v[0:1]
	global_store_dwordx4 v[50:51], v[46:49], off
	ds_read2_b32 v[50:51], v41 offset0:49 offset1:57
	ds_read2_b32 v[52:53], v41 offset0:16 offset1:24
	ds_read2_b32 v[54:55], v41 offset0:82 offset1:90
	ds_read2_b32 v[56:57], v41 offset0:115 offset1:123
	ds_read2_b32 v[58:59], v41 offset0:148 offset1:156
	ds_read2_b32 v[60:61], v41 offset0:181 offset1:189
	ds_read2_b32 v[62:63], v41 offset0:214 offset1:222
	ds_read2_b32 v[64:65], v41 offset0:247 offset1:255
	v_or_b32_e32 v0, s2, v43
	v_lshlrev_b32_e32 v0, 9, v0
	v_lshl_add_u64 v[66:67], v[38:39], 0, v[0:1]
	v_or_b32_e32 v0, s2, v44
	s_waitcnt lgkmcnt(6)
	v_cvt_pk_bf16_f32 v46, v52, v50
	s_waitcnt lgkmcnt(4)
	v_cvt_pk_bf16_f32 v47, v54, v56
	s_waitcnt lgkmcnt(2)
	v_cvt_pk_bf16_f32 v48, v58, v60
	s_waitcnt lgkmcnt(0)
	v_cvt_pk_bf16_f32 v49, v62, v64
	v_lshlrev_b32_e32 v0, 9, v0
	global_store_dwordx4 v[66:67], v[46:49], off
	v_lshl_add_u64 v[38:39], v[38:39], 0, v[0:1]
	s_nop 0
	v_cvt_pk_bf16_f32 v46, v53, v51
	v_cvt_pk_bf16_f32 v47, v55, v57
	v_cvt_pk_bf16_f32 v48, v59, v61
	v_cvt_pk_bf16_f32 v49, v63, v65
	global_store_dwordx4 v[38:39], v[46:49], off
	s_waitcnt lgkmcnt(0)

; __device__ __forceinline__ void transpose_item(const float* __restrict__ W, int K, int N, bf16_t* __restrict__ WT, LAS float* scr, int item, int lane, bool ffn_remap = false) {
;     ...
; #pragma unroll 8
;     for (int i = 0; i < 32; ++i) { const int kk = 2 * i + (lane >> 5); scr[kk * 33 + (lane & 31)] = W[(size_t)(k0 + kk) * N + n0 + (lane & 31)]; }
.LBB0_314:
	s_lshl_b32 s14, s5, 1
	s_lshl_b32 s13, s3, 1
	v_or_b32_e32 v0, s14, v40
	v_or_b32_e32 v46, s13, v7
	v_mov_b32_e32 v47, v1
	v_lshlrev_b64 v[48:49], 12, v[0:1]
	v_lshlrev_b64 v[46:47], 12, v[46:47]
	v_lshl_add_u64 v[48:49], v[38:39], 0, v[48:49]
	v_lshl_add_u64 v[46:47], v[38:39], 0, v[46:47]
	global_load_dword v100, v[48:49], off
	global_load_dword v101, v[46:47], off
	v_or_b32_e32 v45, s13, v5
	v_or_b32_e32 v50, s14, v4
	v_mad_u64_u32 v[116:117], s[16:17], v50, s37, v[8:9]
	v_mad_u64_u32 v[118:119], s[16:17], v45, s37, v[8:9]
	s_add_i32 s16, s14, 4
	s_add_i32 s15, s13, 4
	v_mov_b32_e32 v47, v1
	v_or_b32_e32 v45, s15, v5
	v_or_b32_e32 v50, s16, v4
	s_add_i32 s5, s5, 16
	s_add_i32 s3, s3, 16
	s_add_i32 s12, s12, -16
	v_or_b32_e32 v0, s16, v40
	v_or_b32_e32 v46, s15, v7
	v_lshlrev_b64 v[48:49], 12, v[0:1]
	v_lshlrev_b64 v[46:47], 12, v[46:47]
	v_lshl_add_u64 v[48:49], v[38:39], 0, v[48:49]
	v_lshl_add_u64 v[46:47], v[38:39], 0, v[46:47]
	global_load_dword v102, v[48:49], off
	global_load_dword v103, v[46:47], off
	v_mad_u64_u32 v[120:121], s[16:17], v50, s37, v[8:9]
	v_mad_u64_u32 v[122:123], s[16:17], v45, s37, v[8:9]
	s_add_i32 s16, s14, 8
	s_add_i32 s15, s13, 8
	v_mov_b32_e32 v47, v1
	v_or_b32_e32 v45, s15, v5
	v_or_b32_e32 v50, s16, v4
	v_or_b32_e32 v0, s16, v40
	v_or_b32_e32 v46, s15, v7
	v_lshlrev_b64 v[48:49], 12, v[0:1]
	v_lshlrev_b64 v[46:47], 12, v[46:47]
	v_lshl_add_u64 v[48:49], v[38:39], 0, v[48:49]
	v_lshl_add_u64 v[46:47], v[38:39], 0, v[46:47]
	global_load_dword v104, v[48:49], off
	global_load_dword v105, v[46:47], off
	v_mad_u64_u32 v[124:125], s[16:17], v50, s37, v[8:9]
	v_mad_u64_u32 v[126:127], s[16:17], v45, s37, v[8:9]
	s_add_i32 s16, s14, 12
	s_add_i32 s15, s13, 12
	v_mov_b32_e32 v47, v1
	v_or_b32_e32 v45, s15, v5
	v_or_b32_e32 v50, s16, v4
	v_or_b32_e32 v0, s16, v40
	v_or_b32_e32 v46, s15, v7
	v_lshlrev_b64 v[48:49], 12, v[0:1]
	v_lshlrev_b64 v[46:47], 12, v[46:47]
	v_lshl_add_u64 v[48:49], v[38:39], 0, v[48:49]
	v_lshl_add_u64 v[46:47], v[38:39], 0, v[46:47]
	global_load_dword v106, v[48:49], off
	global_load_dword v107, v[46:47], off
	v_mad_u64_u32 v[128:129], s[16:17], v50, s37, v[8:9]
	v_mad_u64_u32 v[130:131], s[16:17], v45, s37, v[8:9]
	s_add_i32 s16, s14, 16
	s_add_i32 s15, s13, 16
	v_mov_b32_e32 v47, v1
	v_or_b32_e32 v45, s15, v5
	v_or_b32_e32 v50, s16, v4
	v_or_b32_e32 v0, s16, v40
	v_or_b32_e32 v46, s15, v7
	v_lshlrev_b64 v[48:49], 12, v[0:1]
	v_lshlrev_b64 v[46:47], 12, v[46:47]
	v_lshl_add_u64 v[48:49], v[38:39], 0, v[48:49]
	v_lshl_add_u64 v[46:47], v[38:39], 0, v[46:47]
	global_load_dword v108, v[48:49], off
	global_load_dword v109, v[46:47], off
	v_mad_u64_u32 v[132:133], s[16:17], v50, s37, v[8:9]
	v_mad_u64_u32 v[134:135], s[16:17], v45, s37, v[8:9]
	s_add_i32 s16, s14, 20
	s_add_i32 s15, s13, 20
	v_mov_b32_e32 v47, v1
	v_or_b32_e32 v45, s15, v5
	v_or_b32_e32 v50, s16, v4
	v_or_b32_e32 v0, s16, v40
	v_or_b32_e32 v46, s15, v7
	v_lshlrev_b64 v[48:49], 12, v[0:1]
	v_lshlrev_b64 v[46:47], 12, v[46:47]
	v_lshl_add_u64 v[48:49], v[38:39], 0, v[48:49]
	v_lshl_add_u64 v[46:47], v[38:39], 0, v[46:47]
	global_load_dword v110, v[48:49], off
	global_load_dword v111, v[46:47], off
	v_mad_u64_u32 v[136:137], s[16:17], v50, s37, v[8:9]
	v_mad_u64_u32 v[138:139], s[16:17], v45, s37, v[8:9]
	s_add_i32 s16, s14, 24
	s_add_i32 s15, s13, 24
	v_mov_b32_e32 v47, v1
	v_or_b32_e32 v50, s16, v4
	v_or_b32_e32 v45, s15, v5
	s_add_i32 s14, s14, 28
	s_add_i32 s13, s13, 28
	s_cmp_lg_u32 s12, 0
	v_or_b32_e32 v0, s16, v40
	v_or_b32_e32 v46, s15, v7
	v_lshlrev_b64 v[48:49], 12, v[0:1]
	v_lshlrev_b64 v[46:47], 12, v[46:47]
	v_lshl_add_u64 v[48:49], v[38:39], 0, v[48:49]
	v_lshl_add_u64 v[46:47], v[38:39], 0, v[46:47]
	global_load_dword v112, v[48:49], off
	global_load_dword v113, v[46:47], off
	v_mad_u64_u32 v[140:141], s[16:17], v50, s37, v[8:9]
	v_mad_u64_u32 v[142:143], s[16:17], v45, s37, v[8:9]
	v_mov_b32_e32 v47, v1
	v_or_b32_e32 v50, s14, v4
	v_or_b32_e32 v45, s13, v5
	v_or_b32_e32 v0, s14, v40
	v_or_b32_e32 v46, s13, v7
	v_lshlrev_b64 v[48:49], 12, v[0:1]
	v_lshlrev_b64 v[46:47], 12, v[46:47]
	v_lshl_add_u64 v[48:49], v[38:39], 0, v[48:49]
	v_lshl_add_u64 v[46:47], v[38:39], 0, v[46:47]
	global_load_dword v114, v[48:49], off
	global_load_dword v115, v[46:47], off
	v_mad_u64_u32 v[144:145], s[14:15], v50, s37, v[8:9]
	v_mad_u64_u32 v[146:147], s[14:15], v45, s37, v[8:9]
	s_waitcnt vmcnt(15)
	ds_write_b32 v116, v100
	s_waitcnt vmcnt(14)
	ds_write_b32 v118, v101
	s_waitcnt vmcnt(13)
	ds_write_b32 v120, v102
	s_waitcnt vmcnt(12)
	ds_write_b32 v122, v103
	s_waitcnt vmcnt(11)
	ds_write_b32 v124, v104
	s_waitcnt vmcnt(10)
	ds_write_b32 v126, v105
	s_waitcnt vmcnt(9)
	ds_write_b32 v128, v106
	s_waitcnt vmcnt(8)
	ds_write_b32 v130, v107
	s_waitcnt vmcnt(7)
	ds_write_b32 v132, v108
	s_waitcnt vmcnt(6)
	ds_write_b32 v134, v109
	s_waitcnt vmcnt(5)
	ds_write_b32 v136, v110
	s_waitcnt vmcnt(4)
	ds_write_b32 v138, v111
	s_waitcnt vmcnt(3)
	ds_write_b32 v140, v112
	s_waitcnt vmcnt(2)
	ds_write_b32 v142, v113
	s_waitcnt vmcnt(1)
	ds_write_b32 v144, v114
	s_waitcnt vmcnt(0)
	ds_write_b32 v146, v115
	s_cbranch_scc1 .LBB0_314
; #define LAS __attribute__((address_space(3)))
; __device__ __forceinline__ unsigned pk2(float lo, float hi) { f32x2_t v = {lo, hi}; bf16x2_t b = __builtin_convertvector(v, bf16x2_t); return __builtin_bit_cast(unsigned, b); }
; __device__ __forceinline__ void transpose_item(const float* __restrict__ W, int K, int N, bf16_t* __restrict__ WT, LAS float* scr, int item, int lane, bool ffn_remap = false) {
;     ...
;     asm volatile("s_waitcnt lgkmcnt(0)" ::: "memory");
;     const int c = lane & 7;
; #pragma unroll
;     for (int j = 0; j < 4; ++j) { const int n = (lane >> 3) + 8 * j; const LAS float* s = scr + (8 * c) * 33 + n;
;         u32x4 o; o.x = pk2(s[0 * 33], s[1 * 33]); o.y = pk2(s[2 * 33], s[3 * 33]); o.z = pk2(s[4 * 33], s[5 * 33]); o.w = pk2(s[6 * 33], s[7 * 33]);
;         *(u32x4*)(WT + (size_t)(d0 + n) * K + k0 + 8 * c) = o; }
;     asm volatile("s_waitcnt lgkmcnt(0)" ::: "memory");
	s_waitcnt lgkmcnt(0)
	ds_read2_b32 v[50:51], v41 offset0:33 offset1:41
	ds_read2_b32 v[52:53], v41 offset1:8
	ds_read2_b32 v[54:55], v41 offset0:66 offset1:74
	ds_read2_b32 v[56:57], v41 offset0:99 offset1:107
	ds_read2_b32 v[58:59], v41 offset0:132 offset1:140
	ds_read2_b32 v[60:61], v41 offset0:165 offset1:173
	ds_read2_b32 v[62:63], v41 offset0:198 offset1:206
	ds_read2_b32 v[64:65], v41 offset0:231 offset1:239
	s_lshl_b32 s76, s4, 1
	v_or_b32_e32 v0, s2, v9
	v_lshl_add_u64 v[38:39], v[28:29], 0, s[76:77]
	v_lshlrev_b32_e32 v0, 11, v0
	v_lshl_add_u64 v[66:67], v[38:39], 0, v[0:1]
	v_or_b32_e32 v0, s2, v42
	s_waitcnt lgkmcnt(6)
	v_cvt_pk_bf16_f32 v46, v52, v50
	s_waitcnt lgkmcnt(4)
	v_cvt_pk_bf16_f32 v47, v54, v56
	s_waitcnt lgkmcnt(2)
	v_cvt_pk_bf16_f32 v48, v58, v60
	s_waitcnt lgkmcnt(0)
	v_cvt_pk_bf16_f32 v49, v62, v64
	v_lshlrev_b32_e32 v0, 11, v0
	global_store_dwordx4 v[66:67], v[46:49], off
	s_nop 1
	v_cvt_pk_bf16_f32 v46, v53, v51
	v_cvt_pk_bf16_f32 v47, v55, v57
	v_cvt_pk_bf16_f32 v48, v59, v61
	v_cvt_pk_bf16_f32 v49, v63, v65
	v_lshl_add_u64 v[50:51], v[38:39], 0, v[0:1]
	global_store_dwordx4 v[50:51], v[46:49], off
	ds_read2_b32 v[50:51], v41 offset0:49 offset1:57
	ds_read2_b32 v[52:53], v41 offset0:16 offset1:24
	ds_read2_b32 v[54:55], v41 offset0:82 offset1:90
	ds_read2_b32 v[56:57], v41 offset0:115 offset1:123
	ds_read2_b32 v[58:59], v41 offset0:148 offset1:156
	ds_read2_b32 v[60:61], v41 offset0:181 offset1:189
	ds_read2_b32 v[62:63], v41 offset0:214 offset1:222
	ds_read2_b32 v[64:65], v41 offset0:247 offset1:255
	v_or_b32_e32 v0, s2, v43
	v_lshlrev_b32_e32 v0, 11, v0
	v_lshl_add_u64 v[66:67], v[38:39], 0, v[0:1]
	v_or_b32_e32 v0, s2, v44
	s_waitcnt lgkmcnt(6)
	v_cvt_pk_bf16_f32 v46, v52, v50
	s_waitcnt lgkmcnt(4)
	v_cvt_pk_bf16_f32 v47, v54, v56
	s_waitcnt lgkmcnt(2)
	v_cvt_pk_bf16_f32 v48, v58, v60
	s_waitcnt lgkmcnt(0)
	v_cvt_pk_bf16_f32 v49, v62, v64
	v_lshlrev_b32_e32 v0, 11, v0
	global_store_dwordx4 v[66:67], v[46:49], off
	v_lshl_add_u64 v[38:39], v[38:39], 0, v[0:1]
	s_nop 0
	v_cvt_pk_bf16_f32 v46, v53, v51
	v_cvt_pk_bf16_f32 v47, v55, v57
	v_cvt_pk_bf16_f32 v48, v59, v61
	v_cvt_pk_bf16_f32 v49, v63, v65
	global_store_dwordx4 v[38:39], v[46:49], off
	s_waitcnt lgkmcnt(0)

; __device__ __forceinline__ void transpose_item(const float* __restrict__ W, int K, int N, bf16_t* __restrict__ WT, LAS float* scr, int item, int lane, bool ffn_remap = false) {
;     ...
; #pragma unroll 8
;     for (int i = 0; i < 32; ++i) { const int kk = 2 * i + (lane >> 5); scr[kk * 33 + (lane & 31)] = W[(size_t)(k0 + kk) * N + n0 + (lane & 31)]; }
.LBB0_319:
	s_lshl_b32 s14, s5, 1
	s_lshl_b32 s13, s3, 1
	v_or_b32_e32 v0, s14, v40
	v_or_b32_e32 v46, s13, v7
	v_mov_b32_e32 v47, v1
	v_lshlrev_b64 v[48:49], 12, v[0:1]
	v_lshlrev_b64 v[46:47], 12, v[46:47]
	v_lshl_add_u64 v[48:49], v[38:39], 0, v[48:49]
	v_lshl_add_u64 v[46:47], v[38:39], 0, v[46:47]
	global_load_dword v100, v[48:49], off
	global_load_dword v101, v[46:47], off
	v_or_b32_e32 v45, s13, v5
	v_or_b32_e32 v50, s14, v4
	v_mad_u64_u32 v[116:117], s[16:17], v50, s37, v[8:9]
	v_mad_u64_u32 v[118:119], s[16:17], v45, s37, v[8:9]
	s_add_i32 s16, s14, 4
	s_add_i32 s15, s13, 4
	v_mov_b32_e32 v47, v1
	v_or_b32_e32 v45, s15, v5
	v_or_b32_e32 v50, s16, v4
	s_add_i32 s5, s5, 16
	s_add_i32 s3, s3, 16
	s_add_i32 s12, s12, -16
	v_or_b32_e32 v0, s16, v40
	v_or_b32_e32 v46, s15, v7
	v_lshlrev_b64 v[48:49], 12, v[0:1]
	v_lshlrev_b64 v[46:47], 12, v[46:47]
	v_lshl_add_u64 v[48:49], v[38:39], 0, v[48:49]
	v_lshl_add_u64 v[46:47], v[38:39], 0, v[46:47]
	global_load_dword v102, v[48:49], off
	global_load_dword v103, v[46:47], off
	v_mad_u64_u32 v[120:121], s[16:17], v50, s37, v[8:9]
	v_mad_u64_u32 v[122:123], s[16:17], v45, s37, v[8:9]
	s_add_i32 s16, s14, 8
	s_add_i32 s15, s13, 8
	v_mov_b32_e32 v47, v1
	v_or_b32_e32 v45, s15, v5
	v_or_b32_e32 v50, s16, v4
	v_or_b32_e32 v0, s16, v40
	v_or_b32_e32 v46, s15, v7
	v_lshlrev_b64 v[48:49], 12, v[0:1]
	v_lshlrev_b64 v[46:47], 12, v[46:47]
	v_lshl_add_u64 v[48:49], v[38:39], 0, v[48:49]
	v_lshl_add_u64 v[46:47], v[38:39], 0, v[46:47]
	global_load_dword v104, v[48:49], off
	global_load_dword v105, v[46:47], off
	v_mad_u64_u32 v[124:125], s[16:17], v50, s37, v[8:9]
	v_mad_u64_u32 v[126:127], s[16:17], v45, s37, v[8:9]
	s_add_i32 s16, s14, 12
	s_add_i32 s15, s13, 12
	v_mov_b32_e32 v47, v1
	v_or_b32_e32 v45, s15, v5
	v_or_b32_e32 v50, s16, v4
	v_or_b32_e32 v0, s16, v40
	v_or_b32_e32 v46, s15, v7
	v_lshlrev_b64 v[48:49], 12, v[0:1]
	v_lshlrev_b64 v[46:47], 12, v[46:47]
	v_lshl_add_u64 v[48:49], v[38:39], 0, v[48:49]
	v_lshl_add_u64 v[46:47], v[38:39], 0, v[46:47]
	global_load_dword v106, v[48:49], off
	global_load_dword v107, v[46:47], off
	v_mad_u64_u32 v[128:129], s[16:17], v50, s37, v[8:9]
	v_mad_u64_u32 v[130:131], s[16:17], v45, s37, v[8:9]
	s_add_i32 s16, s14, 16
	s_add_i32 s15, s13, 16
	v_mov_b32_e32 v47, v1
	v_or_b32_e32 v45, s15, v5
	v_or_b32_e32 v50, s16, v4
	v_or_b32_e32 v0, s16, v40
	v_or_b32_e32 v46, s15, v7
	v_lshlrev_b64 v[48:49], 12, v[0:1]
	v_lshlrev_b64 v[46:47], 12, v[46:47]
	v_lshl_add_u64 v[48:49], v[38:39], 0, v[48:49]
	v_lshl_add_u64 v[46:47], v[38:39], 0, v[46:47]
	global_load_dword v108, v[48:49], off
	global_load_dword v109, v[46:47], off
	v_mad_u64_u32 v[132:133], s[16:17], v50, s37, v[8:9]
	v_mad_u64_u32 v[134:135], s[16:17], v45, s37, v[8:9]
	s_add_i32 s16, s14, 20
	s_add_i32 s15, s13, 20
	v_mov_b32_e32 v47, v1
	v_or_b32_e32 v45, s15, v5
	v_or_b32_e32 v50, s16, v4
	v_or_b32_e32 v0, s16, v40
	v_or_b32_e32 v46, s15, v7
	v_lshlrev_b64 v[48:49], 12, v[0:1]
	v_lshlrev_b64 v[46:47], 12, v[46:47]
	v_lshl_add_u64 v[48:49], v[38:39], 0, v[48:49]
	v_lshl_add_u64 v[46:47], v[38:39], 0, v[46:47]
	global_load_dword v110, v[48:49], off
	global_load_dword v111, v[46:47], off
	v_mad_u64_u32 v[136:137], s[16:17], v50, s37, v[8:9]
	v_mad_u64_u32 v[138:139], s[16:17], v45, s37, v[8:9]
	s_add_i32 s16, s14, 24
	s_add_i32 s15, s13, 24
	v_mov_b32_e32 v47, v1
	v_or_b32_e32 v50, s16, v4
	v_or_b32_e32 v45, s15, v5
	s_add_i32 s14, s14, 28
	s_add_i32 s13, s13, 28
	s_cmp_lg_u32 s12, 0
	v_or_b32_e32 v0, s16, v40
	v_or_b32_e32 v46, s15, v7
	v_lshlrev_b64 v[48:49], 12, v[0:1]
	v_lshlrev_b64 v[46:47], 12, v[46:47]
	v_lshl_add_u64 v[48:49], v[38:39], 0, v[48:49]
	v_lshl_add_u64 v[46:47], v[38:39], 0, v[46:47]
	global_load_dword v112, v[48:49], off
	global_load_dword v113, v[46:47], off
	v_mad_u64_u32 v[140:141], s[16:17], v50, s37, v[8:9]
	v_mad_u64_u32 v[142:143], s[16:17], v45, s37, v[8:9]
	v_mov_b32_e32 v47, v1
	v_or_b32_e32 v50, s14, v4
	v_or_b32_e32 v45, s13, v5
	v_or_b32_e32 v0, s14, v40
	v_or_b32_e32 v46, s13, v7
	v_lshlrev_b64 v[48:49], 12, v[0:1]
	v_lshlrev_b64 v[46:47], 12, v[46:47]
	v_lshl_add_u64 v[48:49], v[38:39], 0, v[48:49]
	v_lshl_add_u64 v[46:47], v[38:39], 0, v[46:47]
	global_load_dword v114, v[48:49], off
	global_load_dword v115, v[46:47], off
	v_mad_u64_u32 v[144:145], s[14:15], v50, s37, v[8:9]
	v_mad_u64_u32 v[146:147], s[14:15], v45, s37, v[8:9]
	s_waitcnt vmcnt(15)
	ds_write_b32 v116, v100
	s_waitcnt vmcnt(14)
	ds_write_b32 v118, v101
	s_waitcnt vmcnt(13)
	ds_write_b32 v120, v102
	s_waitcnt vmcnt(12)
	ds_write_b32 v122, v103
	s_waitcnt vmcnt(11)
	ds_write_b32 v124, v104
	s_waitcnt vmcnt(10)
	ds_write_b32 v126, v105
	s_waitcnt vmcnt(9)
	ds_write_b32 v128, v106
	s_waitcnt vmcnt(8)
	ds_write_b32 v130, v107
	s_waitcnt vmcnt(7)
	ds_write_b32 v132, v108
	s_waitcnt vmcnt(6)
	ds_write_b32 v134, v109
	s_waitcnt vmcnt(5)
	ds_write_b32 v136, v110
	s_waitcnt vmcnt(4)
	ds_write_b32 v138, v111
	s_waitcnt vmcnt(3)
	ds_write_b32 v140, v112
	s_waitcnt vmcnt(2)
	ds_write_b32 v142, v113
	s_waitcnt vmcnt(1)
	ds_write_b32 v144, v114
	s_waitcnt vmcnt(0)
	ds_write_b32 v146, v115
	s_cbranch_scc1 .LBB0_319
; #define LAS __attribute__((address_space(3)))
; __device__ __forceinline__ unsigned pk2(float lo, float hi) { f32x2_t v = {lo, hi}; bf16x2_t b = __builtin_convertvector(v, bf16x2_t); return __builtin_bit_cast(unsigned, b); }
; __device__ __forceinline__ void transpose_item(const float* __restrict__ W, int K, int N, bf16_t* __restrict__ WT, LAS float* scr, int item, int lane, bool ffn_remap = false) {
;     ...
;     asm volatile("s_waitcnt lgkmcnt(0)" ::: "memory");
;     const int c = lane & 7;
; #pragma unroll
;     for (int j = 0; j < 4; ++j) { const int n = (lane >> 3) + 8 * j; const LAS float* s = scr + (8 * c) * 33 + n;
;         u32x4 o; o.x = pk2(s[0 * 33], s[1 * 33]); o.y = pk2(s[2 * 33], s[3 * 33]); o.z = pk2(s[4 * 33], s[5 * 33]); o.w = pk2(s[6 * 33], s[7 * 33]);
;         *(u32x4*)(WT + (size_t)(d0 + n) * K + k0 + 8 * c) = o; }
;     asm volatile("s_waitcnt lgkmcnt(0)" ::: "memory");
	s_waitcnt lgkmcnt(0)
	ds_read2_b32 v[50:51], v41 offset0:33 offset1:41
	ds_read2_b32 v[52:53], v41 offset1:8
	ds_read2_b32 v[54:55], v41 offset0:66 offset1:74
	ds_read2_b32 v[56:57], v41 offset0:99 offset1:107
	ds_read2_b32 v[58:59], v41 offset0:132 offset1:140
	ds_read2_b32 v[60:61], v41 offset0:165 offset1:173
	ds_read2_b32 v[62:63], v41 offset0:198 offset1:206
	ds_read2_b32 v[64:65], v41 offset0:231 offset1:239
	s_lshl_b32 s76, s4, 1
	v_or_b32_e32 v0, s2, v9
	v_lshl_add_u64 v[38:39], v[32:33], 0, s[76:77]
	v_lshlrev_b32_e32 v0, 13, v0
	v_lshl_add_u64 v[66:67], v[38:39], 0, v[0:1]
	v_or_b32_e32 v0, s2, v42
	s_waitcnt lgkmcnt(6)
	v_cvt_pk_bf16_f32 v46, v52, v50
	s_waitcnt lgkmcnt(4)
	v_cvt_pk_bf16_f32 v47, v54, v56
	s_waitcnt lgkmcnt(2)
	v_cvt_pk_bf16_f32 v48, v58, v60
	s_waitcnt lgkmcnt(0)
	v_cvt_pk_bf16_f32 v49, v62, v64
	v_lshlrev_b32_e32 v0, 13, v0
	global_store_dwordx4 v[66:67], v[46:49], off
	s_nop 1
	v_cvt_pk_bf16_f32 v46, v53, v51
	v_cvt_pk_bf16_f32 v47, v55, v57
	v_cvt_pk_bf16_f32 v48, v59, v61
	v_cvt_pk_bf16_f32 v49, v63, v65
	v_lshl_add_u64 v[50:51], v[38:39], 0, v[0:1]
	global_store_dwordx4 v[50:51], v[46:49], off
	ds_read2_b32 v[50:51], v41 offset0:49 offset1:57
	ds_read2_b32 v[52:53], v41 offset0:16 offset1:24
	ds_read2_b32 v[54:55], v41 offset0:82 offset1:90
	ds_read2_b32 v[56:57], v41 offset0:115 offset1:123
	ds_read2_b32 v[58:59], v41 offset0:148 offset1:156
	ds_read2_b32 v[60:61], v41 offset0:181 offset1:189
	ds_read2_b32 v[62:63], v41 offset0:214 offset1:222
	ds_read2_b32 v[64:65], v41 offset0:247 offset1:255
	v_or_b32_e32 v0, s2, v43
	v_lshlrev_b32_e32 v0, 13, v0
	v_lshl_add_u64 v[66:67], v[38:39], 0, v[0:1]
	v_or_b32_e32 v0, s2, v44
	s_waitcnt lgkmcnt(6)
	v_cvt_pk_bf16_f32 v46, v52, v50
	s_waitcnt lgkmcnt(4)
	v_cvt_pk_bf16_f32 v47, v54, v56
	s_waitcnt lgkmcnt(2)
	v_cvt_pk_bf16_f32 v48, v58, v60
	s_waitcnt lgkmcnt(0)
	v_cvt_pk_bf16_f32 v49, v62, v64
	v_lshlrev_b32_e32 v0, 13, v0
	global_store_dwordx4 v[66:67], v[46:49], off
	v_lshl_add_u64 v[38:39], v[38:39], 0, v[0:1]
	s_nop 0
	v_cvt_pk_bf16_f32 v46, v53, v51
	v_cvt_pk_bf16_f32 v47, v55, v57
	v_cvt_pk_bf16_f32 v48, v59, v61
	v_cvt_pk_bf16_f32 v49, v63, v65
	global_store_dwordx4 v[38:39], v[46:49], off
	s_waitcnt lgkmcnt(0)

; __device__ __forceinline__ void transpose_item(const float* __restrict__ W, int K, int N, bf16_t* __restrict__ WT, LAS float* scr, int item, int lane, bool ffn_remap = false) {
;     ...
; #pragma unroll 8
;     for (int i = 0; i < 32; ++i) { const int kk = 2 * i + (lane >> 5); scr[kk * 33 + (lane & 31)] = W[(size_t)(k0 + kk) * N + n0 + (lane & 31)]; }
.LBB0_323:
	s_lshl_b32 s14, s4, 1
	s_lshl_b32 s13, s3, 1
	v_or_b32_e32 v48, s14, v0
	v_or_b32_e32 v46, s13, v7
	v_ashrrev_i32_e32 v49, 31, v48
	v_ashrrev_i32_e32 v47, 31, v46
	v_lshlrev_b64 v[48:49], 15, v[48:49]
	v_lshlrev_b64 v[46:47], 15, v[46:47]
	v_lshl_add_u64 v[48:49], v[38:39], 0, v[48:49]
	v_lshl_add_u64 v[46:47], v[38:39], 0, v[46:47]
	global_load_dword v100, v[48:49], off
	global_load_dword v101, v[46:47], off
	v_or_b32_e32 v40, s13, v5
	v_or_b32_e32 v45, s14, v4
	v_mad_u64_u32 v[116:117], s[16:17], v45, s37, v[8:9]
	v_mad_u64_u32 v[118:119], s[16:17], v40, s37, v[8:9]
	s_add_i32 s16, s14, 4
	s_add_i32 s15, s13, 4
	v_or_b32_e32 v40, s15, v5
	v_or_b32_e32 v45, s16, v4
	s_add_i32 s4, s4, 16
	s_add_i32 s3, s3, 16
	s_add_i32 s5, s5, -16
	v_or_b32_e32 v48, s16, v0
	v_or_b32_e32 v46, s15, v7
	v_ashrrev_i32_e32 v49, 31, v48
	v_ashrrev_i32_e32 v47, 31, v46
	v_lshlrev_b64 v[48:49], 15, v[48:49]
	v_lshlrev_b64 v[46:47], 15, v[46:47]
	v_lshl_add_u64 v[48:49], v[38:39], 0, v[48:49]
	v_lshl_add_u64 v[46:47], v[38:39], 0, v[46:47]
	global_load_dword v102, v[48:49], off
	global_load_dword v103, v[46:47], off
	v_mad_u64_u32 v[120:121], s[16:17], v45, s37, v[8:9]
	v_mad_u64_u32 v[122:123], s[16:17], v40, s37, v[8:9]
	s_add_i32 s16, s14, 8
	s_add_i32 s15, s13, 8
	v_or_b32_e32 v40, s15, v5
	v_or_b32_e32 v45, s16, v4
	v_or_b32_e32 v48, s16, v0
	v_or_b32_e32 v46, s15, v7
	v_ashrrev_i32_e32 v49, 31, v48
	v_ashrrev_i32_e32 v47, 31, v46
	v_lshlrev_b64 v[48:49], 15, v[48:49]
	v_lshlrev_b64 v[46:47], 15, v[46:47]
	v_lshl_add_u64 v[48:49], v[38:39], 0, v[48:49]
	v_lshl_add_u64 v[46:47], v[38:39], 0, v[46:47]
	global_load_dword v104, v[48:49], off
	global_load_dword v105, v[46:47], off
	v_mad_u64_u32 v[124:125], s[16:17], v45, s37, v[8:9]
	v_mad_u64_u32 v[126:127], s[16:17], v40, s37, v[8:9]
	s_add_i32 s16, s14, 12
	s_add_i32 s15, s13, 12
	v_or_b32_e32 v40, s15, v5
	v_or_b32_e32 v45, s16, v4
	v_or_b32_e32 v48, s16, v0
	v_or_b32_e32 v46, s15, v7
	v_ashrrev_i32_e32 v49, 31, v48
	v_ashrrev_i32_e32 v47, 31, v46
	v_lshlrev_b64 v[48:49], 15, v[48:49]
	v_lshlrev_b64 v[46:47], 15, v[46:47]
	v_lshl_add_u64 v[48:49], v[38:39], 0, v[48:49]
	v_lshl_add_u64 v[46:47], v[38:39], 0, v[46:47]
	global_load_dword v106, v[48:49], off
	global_load_dword v107, v[46:47], off
	v_mad_u64_u32 v[128:129], s[16:17], v45, s37, v[8:9]
	v_mad_u64_u32 v[130:131], s[16:17], v40, s37, v[8:9]
	s_add_i32 s16, s14, 16
	s_add_i32 s15, s13, 16
	v_or_b32_e32 v40, s15, v5
	v_or_b32_e32 v45, s16, v4
	v_or_b32_e32 v48, s16, v0
	v_or_b32_e32 v46, s15, v7
	v_ashrrev_i32_e32 v49, 31, v48
	v_ashrrev_i32_e32 v47, 31, v46
	v_lshlrev_b64 v[48:49], 15, v[48:49]
	v_lshlrev_b64 v[46:47], 15, v[46:47]
	v_lshl_add_u64 v[48:49], v[38:39], 0, v[48:49]
	v_lshl_add_u64 v[46:47], v[38:39], 0, v[46:47]
	global_load_dword v108, v[48:49], off
	global_load_dword v109, v[46:47], off
	v_mad_u64_u32 v[132:133], s[16:17], v45, s37, v[8:9]
	v_mad_u64_u32 v[134:135], s[16:17], v40, s37, v[8:9]
	s_add_i32 s16, s14, 20
	s_add_i32 s15, s13, 20
	v_or_b32_e32 v40, s15, v5
	v_or_b32_e32 v45, s16, v4
	v_or_b32_e32 v48, s16, v0
	v_or_b32_e32 v46, s15, v7
	v_ashrrev_i32_e32 v49, 31, v48
	v_ashrrev_i32_e32 v47, 31, v46
	v_lshlrev_b64 v[48:49], 15, v[48:49]
	v_lshlrev_b64 v[46:47], 15, v[46:47]
	v_lshl_add_u64 v[48:49], v[38:39], 0, v[48:49]
	v_lshl_add_u64 v[46:47], v[38:39], 0, v[46:47]
	global_load_dword v110, v[48:49], off
	global_load_dword v111, v[46:47], off
	v_mad_u64_u32 v[136:137], s[16:17], v45, s37, v[8:9]
	v_mad_u64_u32 v[138:139], s[16:17], v40, s37, v[8:9]
	s_add_i32 s16, s14, 24
	s_add_i32 s15, s13, 24
	v_or_b32_e32 v40, s15, v5
	v_or_b32_e32 v45, s16, v4
	s_add_i32 s14, s14, 28
	s_add_i32 s13, s13, 28
	s_cmp_lg_u32 s5, 0
	v_or_b32_e32 v48, s16, v0
	v_or_b32_e32 v46, s15, v7
	v_ashrrev_i32_e32 v49, 31, v48
	v_ashrrev_i32_e32 v47, 31, v46
	v_lshlrev_b64 v[48:49], 15, v[48:49]
	v_lshlrev_b64 v[46:47], 15, v[46:47]
	v_lshl_add_u64 v[48:49], v[38:39], 0, v[48:49]
	v_lshl_add_u64 v[46:47], v[38:39], 0, v[46:47]
	global_load_dword v112, v[48:49], off
	global_load_dword v113, v[46:47], off
	v_mad_u64_u32 v[140:141], s[16:17], v45, s37, v[8:9]
	v_mad_u64_u32 v[142:143], s[16:17], v40, s37, v[8:9]
	v_or_b32_e32 v45, s14, v4
	v_or_b32_e32 v40, s13, v5
	v_or_b32_e32 v48, s14, v0
	v_or_b32_e32 v46, s13, v7
	v_ashrrev_i32_e32 v49, 31, v48
	v_ashrrev_i32_e32 v47, 31, v46
	v_lshlrev_b64 v[48:49], 15, v[48:49]
	v_lshlrev_b64 v[46:47], 15, v[46:47]
	v_lshl_add_u64 v[48:49], v[38:39], 0, v[48:49]
	v_lshl_add_u64 v[46:47], v[38:39], 0, v[46:47]
	global_load_dword v114, v[48:49], off
	global_load_dword v115, v[46:47], off
	v_mad_u64_u32 v[144:145], s[14:15], v45, s37, v[8:9]
	v_mad_u64_u32 v[146:147], s[14:15], v40, s37, v[8:9]
	s_waitcnt vmcnt(15)
	ds_write_b32 v116, v100
	s_waitcnt vmcnt(14)
	ds_write_b32 v118, v101
	s_waitcnt vmcnt(13)
	ds_write_b32 v120, v102
	s_waitcnt vmcnt(12)
	ds_write_b32 v122, v103
	s_waitcnt vmcnt(11)
	ds_write_b32 v124, v104
	s_waitcnt vmcnt(10)
	ds_write_b32 v126, v105
	s_waitcnt vmcnt(9)
	ds_write_b32 v128, v106
	s_waitcnt vmcnt(8)
	ds_write_b32 v130, v107
	s_waitcnt vmcnt(7)
	ds_write_b32 v132, v108
	s_waitcnt vmcnt(6)
	ds_write_b32 v134, v109
	s_waitcnt vmcnt(5)
	ds_write_b32 v136, v110
	s_waitcnt vmcnt(4)
	ds_write_b32 v138, v111
	s_waitcnt vmcnt(3)
	ds_write_b32 v140, v112
	s_waitcnt vmcnt(2)
	ds_write_b32 v142, v113
	s_waitcnt vmcnt(1)
	ds_write_b32 v144, v114
	s_waitcnt vmcnt(0)
	ds_write_b32 v146, v115
	s_cbranch_scc1 .LBB0_323
; #define LAS __attribute__((address_space(3)))
; __device__ __forceinline__ unsigned pk2(float lo, float hi) { f32x2_t v = {lo, hi}; bf16x2_t b = __builtin_convertvector(v, bf16x2_t); return __builtin_bit_cast(unsigned, b); }
; __device__ __forceinline__ void transpose_item(const float* __restrict__ W, int K, int N, bf16_t* __restrict__ WT, LAS float* scr, int item, int lane, bool ffn_remap = false) {
;     ...
;     const int d0 = !ffn_remap ? n0 : (n0 < 4096 ? (n0 >> 7) * 256 + (n0 & 127) : ((n0 - 4096) >> 7) * 256 + 128 + (n0 & 127));
; #pragma unroll 8
;     for (int i = 0; i < 32; ++i) { const int kk = 2 * i + (lane >> 5); scr[kk * 33 + (lane & 31)] = W[(size_t)(k0 + kk) * N + n0 + (lane & 31)]; }
;     asm volatile("s_waitcnt lgkmcnt(0)" ::: "memory");
;     const int c = lane & 7;
; #pragma unroll
;     for (int j = 0; j < 4; ++j) { const int n = (lane >> 3) + 8 * j; const LAS float* s = scr + (8 * c) * 33 + n;
;         u32x4 o; o.x = pk2(s[0 * 33], s[1 * 33]); o.y = pk2(s[2 * 33], s[3 * 33]); o.z = pk2(s[4 * 33], s[5 * 33]); o.w = pk2(s[6 * 33], s[7 * 33]);
;         *(u32x4*)(WT + (size_t)(d0 + n) * K + k0 + 8 * c) = o; }
;     asm volatile("s_waitcnt lgkmcnt(0)" ::: "memory");
	s_lshl_b32 s3, s2, 6
	s_and_b32 s4, s3, 0x7fffff00
	s_and_b32 s3, s3, 0xffffff00
	s_and_b32 s5, s26, 0x60
	s_addk_i32 s4, 0xe080
	s_cmpk_lt_i32 s2, 0x80
	s_waitcnt lgkmcnt(0)
	s_cselect_b32 s2, s3, s4
	ds_read2_b32 v[50:51], v41 offset0:33 offset1:41
	ds_read2_b32 v[52:53], v41 offset1:8
	ds_read2_b32 v[54:55], v41 offset0:66 offset1:74
	ds_read2_b32 v[56:57], v41 offset0:99 offset1:107
	ds_read2_b32 v[58:59], v41 offset0:132 offset1:140
	ds_read2_b32 v[60:61], v41 offset0:165 offset1:173
	ds_read2_b32 v[62:63], v41 offset0:198 offset1:206
	ds_read2_b32 v[64:65], v41 offset0:231 offset1:239
	s_or_b32 s2, s2, s5
	v_or_b32_e32 v66, s2, v9
	s_ashr_i32 s13, s12, 31
	v_ashrrev_i32_e32 v67, 31, v66
	v_lshl_add_u64 v[38:39], s[12:13], 1, v[36:37]
	v_lshlrev_b64 v[66:67], 11, v[66:67]
	s_waitcnt lgkmcnt(6)
	v_cvt_pk_bf16_f32 v46, v52, v50
	s_waitcnt lgkmcnt(4)
	v_cvt_pk_bf16_f32 v47, v54, v56
	s_waitcnt lgkmcnt(2)
	v_cvt_pk_bf16_f32 v48, v58, v60
	s_waitcnt lgkmcnt(0)
	v_cvt_pk_bf16_f32 v49, v62, v64
	v_lshl_add_u64 v[66:67], v[38:39], 0, v[66:67]
	v_or_b32_e32 v50, s2, v42
	global_store_dwordx4 v[66:67], v[46:49], off
	v_or_b32_e32 v66, s2, v43
	v_ashrrev_i32_e32 v67, 31, v66
	v_cvt_pk_bf16_f32 v46, v53, v51
	v_ashrrev_i32_e32 v51, 31, v50
	v_lshlrev_b64 v[50:51], 11, v[50:51]
	v_cvt_pk_bf16_f32 v47, v55, v57
	v_cvt_pk_bf16_f32 v48, v59, v61
	v_cvt_pk_bf16_f32 v49, v63, v65
	v_lshl_add_u64 v[50:51], v[38:39], 0, v[50:51]
	global_store_dwordx4 v[50:51], v[46:49], off
	ds_read2_b32 v[50:51], v41 offset0:49 offset1:57
	ds_read2_b32 v[52:53], v41 offset0:16 offset1:24
	ds_read2_b32 v[54:55], v41 offset0:82 offset1:90
	ds_read2_b32 v[56:57], v41 offset0:115 offset1:123
	ds_read2_b32 v[58:59], v41 offset0:148 offset1:156
	ds_read2_b32 v[60:61], v41 offset0:181 offset1:189
	ds_read2_b32 v[62:63], v41 offset0:214 offset1:222
	ds_read2_b32 v[64:65], v41 offset0:247 offset1:255
	v_lshlrev_b64 v[66:67], 11, v[66:67]
	s_waitcnt lgkmcnt(6)
	v_cvt_pk_bf16_f32 v46, v52, v50
	s_waitcnt lgkmcnt(4)
	v_cvt_pk_bf16_f32 v47, v54, v56
	s_waitcnt lgkmcnt(2)
	v_cvt_pk_bf16_f32 v48, v58, v60
	s_waitcnt lgkmcnt(0)
	v_cvt_pk_bf16_f32 v49, v62, v64
	v_lshl_add_u64 v[66:67], v[38:39], 0, v[66:67]
	v_or_b32_e32 v50, s2, v44
	global_store_dwordx4 v[66:67], v[46:49], off
	s_nop 1
	v_cvt_pk_bf16_f32 v46, v53, v51
	v_ashrrev_i32_e32 v51, 31, v50
	v_lshlrev_b64 v[50:51], 11, v[50:51]
	v_cvt_pk_bf16_f32 v47, v55, v57
	v_cvt_pk_bf16_f32 v48, v59, v61
	v_cvt_pk_bf16_f32 v49, v63, v65
	v_lshl_add_u64 v[38:39], v[38:39], 0, v[50:51]
	global_store_dwordx4 v[38:39], v[46:49], off
	s_waitcnt lgkmcnt(0)
	s_branch .LBB0_276
